# GEMM unit transitions: first-iteration waits of phases I/II relaxed to vmcnt(24) for units that follow an epilogue (store acks decoupled from the next unit's first MFMA phases)
# speedup vs baseline: 1.0013x; 1.0013x over previous
; #define PG8_STAGE(bufoff, gbase, voff) do { _Pragma("unroll") for (int _i = 0; _i < 2; ++_i) \
;         __builtin_amdgcn_global_load_lds((const unsigned*)((const char*)(gbase) + (voff)[_i]), (LAS unsigned*)(lds + (bufoff) + ldsw + _i * 8192), 16, 0, 0); } while (0)
; #define PG8_WAIT_V(n) asm volatile("s_waitcnt vmcnt(" #n ")" ::: "memory")
; #define PG8_BAR __builtin_amdgcn_s_barrier()
; template <class Epi>
; __device__ __forceinline__ void gemm_phase(LAS unsigned char* lds, const Gemm g, const StaticOrder& S, const Epi& E) {
;     ...
;     for (int i = 0; i < 2; ++i) { int R, C; stage_rc(tid * 16 + i * 8192, R, C); const int Rb = Epi::PERM ? ((R & ~31) + perm32(R & 31)) : R;
;         voffA[i] = (unsigned)(R * lda + C) * 2u; voffB[i] = (unsigned)(Rb * K + C) * 2u; }
;     const size_t kstep = (size_t)(BK * 2);
;     const size_t hstepA = (size_t)HALF * lda * 2, hstepB = (size_t)HALF * K * 2;
;     const size_t tstepA = 2 * hstepA, tstepB = 2 * hstepB;
;     const unsigned ldsw = (unsigned)wid * 1024u;
;     const int aoff = lds_byte(wr * 64 + fr, fq * 8), boff = lds_byte(wc * 32 + fr, fq * 8);
;     ...
;     Unit cur, nxt; int ui = 0;
;     if (!S.next(0, cur)) return;
;     f32x4 acc[2][2][4][2];
; #pragma unroll
;     for (int a = 0; a < 2; ++a)
; #pragma unroll
;         for (int b = 0; b < 2; ++b)
; #pragma unroll
;             for (int m = 0; m < 4; ++m)
; #pragma unroll
;                 for (int n = 0; n < 2; ++n) acc[a][b][m][n] = (f32x4){0.f, 0.f, 0.f, 0.f};
;     bf16x8 At[4][2], B0[2][2], B1[2][2];
;     const char* cA = (const char*)g.A + (size_t)cur.pm * tstepA + (size_t)cur.kt0 * kstep; const char* cB = (const char*)g.Bt + (size_t)cur.pn * tstepB + (size_t)cur.kt0 * kstep;
;     PG8_STAGE(PG8_SB(0, 0), cB, voffB); PG8_STAGE(PG8_SA(0, 0), cA, voffA); PG8_STAGE(PG8_SB(0, 1), cB + hstepB, voffB); PG8_STAGE(PG8_SA(0, 1), cA + hstepA, voffA);
;     if (wr == 1) PG8_BAR;
;     PG8_WAIT_V(4); PG8_BAR;
;     PG8_STAGE(PG8_SB(1, 0), cB + kstep, voffB); PG8_STAGE(PG8_SA(1, 0), cA + kstep, voffA); PG8_STAGE(PG8_SB(1, 1), cB + hstepB + kstep, voffB);
;     PG8_WAIT_V(6); PG8_BAR;
.LBB0_110:
	s_lshl_b32 s7, s7, 5
	s_mov_b64 s[28:29], 0x80
	s_and_b32 s7, s7, 0x60
	s_add_i32 m0, s68, 0x18000
	v_lshl_add_u64 v[6:7], v[6:7], 0, s[28:29]
	s_lshl_b32 s9, s6, 13
	s_lshl_b32 s33, s7, 7
	s_waitcnt vmcnt(0)
	s_barrier
	global_load_lds_dwordx4 v[6:7], off
	v_lshl_add_u64 v[4:5], v[4:5], 0, s[28:29]
	s_add_i32 m0, s68, 0x1a000
	s_add_i32 s73, s68, 0x8000
	s_add_i32 s74, s68, 0xa000
	global_load_lds_dwordx4 v[4:5], off
	v_lshl_add_u64 v[2:3], v[2:3], 0, s[28:29]
	s_mov_b32 m0, s73
	s_add_u32 s30, s64, 0x40080
	global_load_lds_dwordx4 v[2:3], off
	v_lshl_add_u64 v[0:1], v[0:1], 0, s[28:29]
	s_mov_b32 m0, s74
	s_addc_u32 s31, s65, 0
	global_load_lds_dwordx4 v[0:1], off
	s_add_i32 m0, s68, 0x1c000
	v_lshl_add_u64 v[0:1], s[30:31], 0, v[132:133]
	global_load_lds_dwordx4 v[0:1], off
	v_lshl_add_u64 v[0:1], s[30:31], 0, v[136:137]
	s_add_i32 m0, s68, 0x1e000
	v_lshlrev_b32_e32 v2, 2, v129
	global_load_lds_dwordx4 v[0:1], off
	v_and_b32_e32 v0, 15, v129
	v_lshl_or_b32 v151, s6, 6, v0
	v_lshlrev_b32_e32 v1, 1, v11
	v_lshlrev_b32_e32 v3, 6, v129
	s_movk_i32 s6, 0x3c0
	v_lshl_or_b32 v0, v0, 6, v1
	v_and_b32_e32 v2, 32, v2
	v_and_or_b32 v1, v3, s6, v1
	v_bitop3_b32 v152, s33, v1, v2 bitop3:0xf6
	v_lshlrev_b32_e32 v1, 8, v129
	v_bitop3_b32 v0, v0, s9, v2 bitop3:0xde
	v_and_b32_e32 v1, 0x38000, v1
	v_lshlrev_b32_e32 v2, 11, v10
	v_or3_b32 v1, v8, v1, v2
	v_add_u32_e32 v138, v1, v9
	v_lshlrev_b32_e32 v1, 4, v12
	s_waitcnt vmcnt(6)
	v_and_b32_e32 v1, 0x78000, v1
	v_or3_b32 v1, v8, v1, v2
	s_add_i32 s78, 0, 0x10000
	s_add_i32 s79, 0, 0x14000
	s_ashr_i32 s75, s14, 31
	s_mov_b32 s76, s14
	s_ashr_i32 s77, s2, 31
	v_or_b32_e32 v153, s7, v11
	v_mov_b32_e32 v139, v133
	v_add_u32_e32 v140, v1, v9
	v_mov_b32_e32 v141, v133
	v_mov_b64_e32 v[142:143], 0x2d6
	v_mov_b64_e32 v[144:145], 0x2d5
	v_add_u32_e32 v154, s78, v152
	v_add_u32_e32 v155, 0, v0
	v_add_u32_e32 v156, s79, v152
	s_movk_i32 s80, 0x60f
	s_movk_i32 s81, 0x1600
	s_barrier
	s_mov_b32 s99, 0
	s_branch .LBB0_112

; #define PG8_STAGE(bufoff, gbase, voff) do { _Pragma("unroll") for (int _i = 0; _i < 2; ++_i) \
;         __builtin_amdgcn_global_load_lds((const unsigned*)((const char*)(gbase) + (voff)[_i]), (LAS unsigned*)(lds + (bufoff) + ldsw + _i * 8192), 16, 0, 0); } while (0)
; #define PG8_LDA(dst, b, h) do { _Pragma("unroll") for (int m = 0; m < 4; ++m) _Pragma("unroll") for (int k = 0; k < 2; ++k) dst[m][k] = *(const LAS bf16x8*)(lds + PG8_SA(b, h) + aoff + m * 2048 + k * 1024); } while (0)
; #define PG8_LDB(dst, b, h) do { _Pragma("unroll") for (int n = 0; n < 2; ++n) _Pragma("unroll") for (int k = 0; k < 2; ++k) dst[n][k] = *(const LAS bf16x8*)(lds + PG8_SB(b, h) + boff + n * 2048 + k * 1024); } while (0)
; #define PG8_MMA(ai, bj, At, Bt) do { __builtin_amdgcn_s_setprio(1); _Pragma("unroll") for (int m = 0; m < 4; ++m) _Pragma("unroll") for (int n = 0; n < 2; ++n) _Pragma("unroll") for (int k = 0; k < 2; ++k) \
;         acc[ai][bj][m][n] = __builtin_amdgcn_mfma_f32_16x16x32_bf16(Bt[n][k], At[m][k], acc[ai][bj][m][n], 0, 0, 0); __builtin_amdgcn_s_setprio(0); } while (0)
; template <class Epi>
; __device__ __forceinline__ void gemm_phase(LAS unsigned char* lds, const Gemm g, const StaticOrder& S, const Epi& E) {
;     ...
;         const bool has_next = S.next(ui + 1, nxt);
;         const char* nA = has_next ? (const char*)g.A + (size_t)nxt.pm * tstepA + (size_t)nxt.kt0 * kstep : cA; const char* nB = has_next ? (const char*)g.Bt + (size_t)nxt.pn * tstepB + (size_t)nxt.kt0 * kstep : cB;
;         const int nt = cur.nkt;
;         for (int t = 0; t < nt; t += 2) {
;             const bool last = (t == nt - 2);
;             const char* a1 = cA + (size_t)(t + 1) * kstep;
;             const char* a2 = last ? nA : cA + (size_t)(t + 2) * kstep; const char* b2 = last ? nB : cB + (size_t)(t + 2) * kstep;
;             const char* a3 = a2 + kstep; const char* b3 = b2 + kstep;
;             PG8_LDB(B0, 0, 0); PG8_SCHED; PG8_LDA(At, 0, 0); PG8_STAGE(PG8_SA(1, 1), a1 + hstepA, voffA);
;             PG8_WAIT_L(8); PG8_BAR; PG8_WAIT_L(0); PG8_MMA(0, 0, At, B0); PG8_BAR; PG8_SCHED;
;             PG8_LDB(B1, 0, 1); PG8_STAGE(PG8_SB(0, 0), b2, voffB);
;             PG8_BAR; PG8_WAIT_L(0); PG8_MMA(0, 1, At, B1); PG8_BAR;
;             PG8_LDA(At, 0, 1); PG8_STAGE(PG8_SA(0, 0), a2, voffA);
;             PG8_BAR; PG8_WAIT_L(0); PG8_MMA(1, 0, At, B0); PG8_BAR; PG8_SCHED;
.LBB0_118:
	s_ashr_i32 s55, s54, 31
	v_cmp_lt_i64_e32 vcc, s[56:57], v[142:143]
	s_lshl_b64 s[56:57], s[54:55], 19
	s_add_u32 s9, s52, s56
	s_addc_u32 s31, s53, s57
	s_and_b64 s[56:57], vcc, exec
	s_cselect_b32 s57, s31, s63
	s_cselect_b32 s56, s9, s62
	s_ashr_i32 s31, s30, 31
	s_lshl_b64 s[58:59], s[30:31], 19
	s_add_u32 s9, s92, s58
	s_addc_u32 s31, s93, s59
	s_and_b64 s[58:59], vcc, exec
	s_cselect_b32 s59, s31, s65
	s_cselect_b32 s58, s9, s64
	s_add_u32 s62, s62, 0x40080
	s_addc_u32 s63, s63, 0
	s_add_u32 s9, s64, 0x100
	s_addc_u32 s31, s65, 0
	s_mov_b32 s33, -2
	s_add_u32 s55, s62, 0xfffc0080
	s_addc_u32 s61, s63, -1
	s_cmp_eq_u32 s33, 12
	s_cselect_b32 s67, s57, s61
	s_cselect_b32 s66, s56, s55
	s_cselect_b32 s65, s59, s31
	s_cselect_b32 s64, s58, s9
	ds_read_b128 v[146:149], v154
	ds_read_b128 v[158:161], v154 offset:1024
	ds_read_b128 v[162:165], v154 offset:2048
	ds_read_b128 v[166:169], v154 offset:3072
	ds_read_b128 v[170:173], v155
	ds_read_b128 v[174:177], v155 offset:1024
	ds_read_b128 v[178:181], v155 offset:2048
	ds_read_b128 v[182:185], v155 offset:3072
	ds_read_b128 v[186:189], v155 offset:4096
	ds_read_b128 v[190:193], v155 offset:5120
	ds_read_b128 v[194:197], v155 offset:6144
	ds_read_b128 v[198:201], v155 offset:7168
	ds_read_b128 v[202:205], v156
	ds_read_b128 v[206:209], v156 offset:1024
	ds_read_b128 v[210:213], v156 offset:2048
	ds_read_b128 v[214:217], v156 offset:3072
	s_add_i32 m0, s68, 0xc000
	v_lshl_add_u64 v[242:243], s[62:63], 0, v[138:139]
	global_load_lds_dwordx4 v[242:243], off
	s_add_i32 m0, s68, 0xe000
	v_lshl_add_u64 v[242:243], s[62:63], 0, v[140:141]
	global_load_lds_dwordx4 v[242:243], off
	s_cmp_eq_u32 s99, 0
	s_cbranch_scc1 .Lrw0_0s
	s_waitcnt vmcnt(24) lgkmcnt(0)
	s_branch .Lrw0_0d
.Lrw0_0s:
	s_waitcnt vmcnt(8) lgkmcnt(0)
.Lrw0_0d:
	s_barrier
	v_mfma_f32_16x16x32_bf16 v[124:127], v[146:149], v[170:173], 0
	v_mfma_f32_16x16x32_bf16 v[120:123], v[162:165], v[170:173], 0
	v_mfma_f32_16x16x32_bf16 v[108:111], v[146:149], v[178:181], 0
	v_mfma_f32_16x16x32_bf16 v[104:107], v[162:165], v[178:181], 0
	v_mfma_f32_16x16x32_bf16 v[92:95], v[146:149], v[186:189], 0
	v_mfma_f32_16x16x32_bf16 v[88:91], v[162:165], v[186:189], 0
	v_mfma_f32_16x16x32_bf16 v[76:79], v[146:149], v[194:197], 0
	v_mfma_f32_16x16x32_bf16 v[72:75], v[162:165], v[194:197], 0
	v_mfma_f32_16x16x32_bf16 v[124:127], v[158:161], v[174:177], v[124:127]
	v_mfma_f32_16x16x32_bf16 v[120:123], v[166:169], v[174:177], v[120:123]
	v_mfma_f32_16x16x32_bf16 v[108:111], v[158:161], v[182:185], v[108:111]
	v_mfma_f32_16x16x32_bf16 v[104:107], v[166:169], v[182:185], v[104:107]
	v_mfma_f32_16x16x32_bf16 v[92:95], v[158:161], v[190:193], v[92:95]
	v_mfma_f32_16x16x32_bf16 v[88:91], v[166:169], v[190:193], v[88:91]
	v_mfma_f32_16x16x32_bf16 v[76:79], v[158:161], v[198:201], v[76:79]
	v_mfma_f32_16x16x32_bf16 v[72:75], v[166:169], v[198:201], v[72:75]
	v_mfma_f32_16x16x32_bf16 v[116:119], v[202:205], v[170:173], 0
	v_mfma_f32_16x16x32_bf16 v[112:115], v[210:213], v[170:173], 0
	v_mfma_f32_16x16x32_bf16 v[100:103], v[202:205], v[178:181], 0
	v_mfma_f32_16x16x32_bf16 v[96:99], v[210:213], v[178:181], 0
	v_mfma_f32_16x16x32_bf16 v[84:87], v[202:205], v[186:189], 0
	v_mfma_f32_16x16x32_bf16 v[80:83], v[210:213], v[186:189], 0
	v_mfma_f32_16x16x32_bf16 v[68:71], v[202:205], v[194:197], 0
	v_mfma_f32_16x16x32_bf16 v[64:67], v[210:213], v[194:197], 0
	v_mfma_f32_16x16x32_bf16 v[116:119], v[206:209], v[174:177], v[116:119]
	v_mfma_f32_16x16x32_bf16 v[112:115], v[214:217], v[174:177], v[112:115]
	v_mfma_f32_16x16x32_bf16 v[100:103], v[206:209], v[182:185], v[100:103]
	v_mfma_f32_16x16x32_bf16 v[96:99], v[214:217], v[182:185], v[96:99]
	v_mfma_f32_16x16x32_bf16 v[84:87], v[206:209], v[190:193], v[84:87]
	v_mfma_f32_16x16x32_bf16 v[80:83], v[214:217], v[190:193], v[80:83]
	v_mfma_f32_16x16x32_bf16 v[68:71], v[206:209], v[198:201], v[68:71]
	v_mfma_f32_16x16x32_bf16 v[64:67], v[214:217], v[198:201], v[64:67]
	s_barrier
	ds_read_b128 v[170:173], v155 offset:16384
	ds_read_b128 v[174:177], v155 offset:17408
	ds_read_b128 v[178:181], v155 offset:18432
	ds_read_b128 v[182:185], v155 offset:19456
	ds_read_b128 v[186:189], v155 offset:20480
	ds_read_b128 v[190:193], v155 offset:21504
	ds_read_b128 v[194:197], v155 offset:22528
	ds_read_b128 v[198:201], v155 offset:23552
	s_add_i32 s55, s78, s35
	s_mov_b32 m0, s55
	v_lshl_add_u64 v[218:219], s[64:65], 0, v[132:133]
	global_load_lds_dwordx4 v[218:219], off
	s_add_i32 m0, s55, 0x2000
	v_lshl_add_u64 v[220:221], s[64:65], 0, v[136:137]
	global_load_lds_dwordx4 v[220:221], off
	s_mov_b32 m0, s68
	v_lshl_add_u64 v[222:223], s[66:67], 0, v[130:131]
	global_load_lds_dwordx4 v[222:223], off
	s_mov_b32 m0, s69
	v_lshl_add_u64 v[224:225], s[66:67], 0, v[134:135]
	global_load_lds_dwordx4 v[224:225], off
	s_add_u32 s82, s64, 0x40000
	s_addc_u32 s83, s65, 0
	s_add_i32 s55, s79, s35
	s_mov_b32 m0, s55
	v_lshl_add_u64 v[240:241], s[82:83], 0, v[132:133]
	global_load_lds_dwordx4 v[240:241], off
	s_add_i32 m0, s55, 0x2000
	v_lshl_add_u64 v[240:241], s[82:83], 0, v[136:137]
	global_load_lds_dwordx4 v[240:241], off
	s_cmp_eq_u32 s99, 0
	s_cbranch_scc1 .Lrw0_1s
	s_waitcnt vmcnt(24) lgkmcnt(0)
	s_branch .Lrw0_1d

; #define PG8_STAGE(bufoff, gbase, voff) do { _Pragma("unroll") for (int _i = 0; _i < 2; ++_i) \
;         __builtin_amdgcn_global_load_lds((const unsigned*)((const char*)(gbase) + (voff)[_i]), (LAS unsigned*)(lds + (bufoff) + ldsw + _i * 8192), 16, 0, 0); } while (0)
; #define PG8_LDA(dst, b, h) do { _Pragma("unroll") for (int m = 0; m < 4; ++m) _Pragma("unroll") for (int k = 0; k < 2; ++k) dst[m][k] = *(const LAS bf16x8*)(lds + PG8_SA(b, h) + aoff + m * 2048 + k * 1024); } while (0)
; #define PG8_LDB(dst, b, h) do { _Pragma("unroll") for (int n = 0; n < 2; ++n) _Pragma("unroll") for (int k = 0; k < 2; ++k) dst[n][k] = *(const LAS bf16x8*)(lds + PG8_SB(b, h) + boff + n * 2048 + k * 1024); } while (0)
; #define PG8_MMA(ai, bj, At, Bt) do { __builtin_amdgcn_s_setprio(1); _Pragma("unroll") for (int m = 0; m < 4; ++m) _Pragma("unroll") for (int n = 0; n < 2; ++n) _Pragma("unroll") for (int k = 0; k < 2; ++k) \
;         acc[ai][bj][m][n] = __builtin_amdgcn_mfma_f32_16x16x32_bf16(Bt[n][k], At[m][k], acc[ai][bj][m][n], 0, 0, 0); __builtin_amdgcn_s_setprio(0); } while (0)
; #define PG8_WAIT_V(n) asm volatile("s_waitcnt vmcnt(" #n ")" ::: "memory")
; #define PG8_WAIT_L(n) asm volatile("s_waitcnt lgkmcnt(" #n ")" ::: "memory")
; #define PG8_BAR __builtin_amdgcn_s_barrier()
; #define PG8_SCHED __builtin_amdgcn_sched_barrier(0)
; template <class Epi>
; __device__ __forceinline__ void gemm_phase(LAS unsigned char* lds, const Gemm g, const StaticOrder& S, const Epi& E) {
;     ...
;             PG8_BAR; PG8_WAIT_L(0); PG8_MMA(0, 1, At, B1); PG8_BAR;
;             PG8_LDA(At, 0, 1); PG8_STAGE(PG8_SA(0, 0), a2, voffA);
;             PG8_BAR; PG8_WAIT_L(0); PG8_MMA(1, 0, At, B0); PG8_BAR; PG8_SCHED;
;             PG8_STAGE(PG8_SB(0, 1), b2 + hstepB, voffB);
;             PG8_WAIT_V(6); PG8_BAR; PG8_MMA(1, 1, At, B1); PG8_BAR;
;             PG8_LDB(B0, 1, 0); PG8_SCHED; PG8_LDA(At, 1, 0); PG8_STAGE(PG8_SA(0, 1), a2 + hstepA, voffA);
;             PG8_WAIT_L(8); PG8_BAR; PG8_WAIT_L(0); PG8_MMA(0, 0, At, B0); PG8_BAR; PG8_SCHED;
.Lrw0_1d:
	s_mov_b32 s99, 1
	s_barrier
	v_mfma_f32_16x16x32_bf16 v[60:63], v[146:149], v[170:173], 0
	v_mfma_f32_16x16x32_bf16 v[56:59], v[162:165], v[170:173], 0
	v_mfma_f32_16x16x32_bf16 v[44:47], v[146:149], v[178:181], 0
	v_mfma_f32_16x16x32_bf16 v[40:43], v[162:165], v[178:181], 0
	v_mfma_f32_16x16x32_bf16 v[28:31], v[146:149], v[186:189], 0
	v_mfma_f32_16x16x32_bf16 v[24:27], v[162:165], v[186:189], 0
	v_mfma_f32_16x16x32_bf16 v[12:15], v[146:149], v[194:197], 0
	v_mfma_f32_16x16x32_bf16 v[8:11], v[162:165], v[194:197], 0
	v_mfma_f32_16x16x32_bf16 v[60:63], v[158:161], v[174:177], v[60:63]
	v_mfma_f32_16x16x32_bf16 v[56:59], v[166:169], v[174:177], v[56:59]
	v_mfma_f32_16x16x32_bf16 v[44:47], v[158:161], v[182:185], v[44:47]
	v_mfma_f32_16x16x32_bf16 v[40:43], v[166:169], v[182:185], v[40:43]
	v_mfma_f32_16x16x32_bf16 v[28:31], v[158:161], v[190:193], v[28:31]
	v_mfma_f32_16x16x32_bf16 v[24:27], v[166:169], v[190:193], v[24:27]
	v_mfma_f32_16x16x32_bf16 v[12:15], v[158:161], v[198:201], v[12:15]
	v_mfma_f32_16x16x32_bf16 v[8:11], v[166:169], v[198:201], v[8:11]
	v_mfma_f32_16x16x32_bf16 v[52:55], v[202:205], v[170:173], 0
	v_mfma_f32_16x16x32_bf16 v[48:51], v[210:213], v[170:173], 0
	v_mfma_f32_16x16x32_bf16 v[36:39], v[202:205], v[178:181], 0
	v_mfma_f32_16x16x32_bf16 v[32:35], v[210:213], v[178:181], 0
	v_mfma_f32_16x16x32_bf16 v[20:23], v[202:205], v[186:189], 0
	v_mfma_f32_16x16x32_bf16 v[16:19], v[210:213], v[186:189], 0
	v_mfma_f32_16x16x32_bf16 v[4:7], v[202:205], v[194:197], 0
	v_mfma_f32_16x16x32_bf16 v[0:3], v[210:213], v[194:197], 0
	v_mfma_f32_16x16x32_bf16 v[52:55], v[206:209], v[174:177], v[52:55]
	v_mfma_f32_16x16x32_bf16 v[48:51], v[214:217], v[174:177], v[48:51]
	v_mfma_f32_16x16x32_bf16 v[36:39], v[206:209], v[182:185], v[36:39]
	v_mfma_f32_16x16x32_bf16 v[32:35], v[214:217], v[182:185], v[32:35]
	v_mfma_f32_16x16x32_bf16 v[20:23], v[206:209], v[190:193], v[20:23]
	v_mfma_f32_16x16x32_bf16 v[16:19], v[214:217], v[190:193], v[16:19]
	v_mfma_f32_16x16x32_bf16 v[4:7], v[206:209], v[198:201], v[4:7]
	v_mfma_f32_16x16x32_bf16 v[0:3], v[214:217], v[198:201], v[0:3]
	s_barrier
	s_add_i32 s55, 0, 0x18000
	v_add_u32_e32 v157, s55, v152
	ds_read_b128 v[146:149], v157
	ds_read_b128 v[158:161], v157 offset:1024
	ds_read_b128 v[162:165], v157 offset:2048
	ds_read_b128 v[166:169], v157 offset:3072
	ds_read_b128 v[170:173], v155 offset:32768
	ds_read_b128 v[174:177], v155 offset:33792
	ds_read_b128 v[178:181], v155 offset:34816
	ds_read_b128 v[182:185], v155 offset:35840
	ds_read_b128 v[186:189], v155 offset:36864
	ds_read_b128 v[190:193], v155 offset:37888
	ds_read_b128 v[194:197], v155 offset:38912
	ds_read_b128 v[198:201], v155 offset:39936
	s_add_i32 s98, 0, 0x1c000
	v_add_u32_e32 v246, s98, v152
	ds_read_b128 v[202:205], v246
	ds_read_b128 v[206:209], v246 offset:1024
	ds_read_b128 v[210:213], v246 offset:2048
	ds_read_b128 v[214:217], v246 offset:3072
	s_add_u32 s66, s66, 0x40000
	s_addc_u32 s67, s67, 0
	s_mov_b32 m0, s70
	v_lshl_add_u64 v[244:245], s[66:67], 0, v[130:131]
	global_load_lds_dwordx4 v[244:245], off
	s_mov_b32 m0, s71
	v_lshl_add_u64 v[244:245], s[66:67], 0, v[134:135]
	global_load_lds_dwordx4 v[244:245], off
	s_waitcnt vmcnt(8) lgkmcnt(0)
	s_barrier
	v_mfma_f32_16x16x32_bf16 v[124:127], v[146:149], v[170:173], v[124:127]
	v_mfma_f32_16x16x32_bf16 v[120:123], v[162:165], v[170:173], v[120:123]
	v_mfma_f32_16x16x32_bf16 v[108:111], v[146:149], v[178:181], v[108:111]
	v_mfma_f32_16x16x32_bf16 v[104:107], v[162:165], v[178:181], v[104:107]
	v_mfma_f32_16x16x32_bf16 v[92:95], v[146:149], v[186:189], v[92:95]
	v_mfma_f32_16x16x32_bf16 v[88:91], v[162:165], v[186:189], v[88:91]
	v_mfma_f32_16x16x32_bf16 v[76:79], v[146:149], v[194:197], v[76:79]
	v_mfma_f32_16x16x32_bf16 v[72:75], v[162:165], v[194:197], v[72:75]
	v_mfma_f32_16x16x32_bf16 v[124:127], v[158:161], v[174:177], v[124:127]
	v_mfma_f32_16x16x32_bf16 v[120:123], v[166:169], v[174:177], v[120:123]
	v_mfma_f32_16x16x32_bf16 v[108:111], v[158:161], v[182:185], v[108:111]
	v_mfma_f32_16x16x32_bf16 v[104:107], v[166:169], v[182:185], v[104:107]
	v_mfma_f32_16x16x32_bf16 v[92:95], v[158:161], v[190:193], v[92:95]
	v_mfma_f32_16x16x32_bf16 v[88:91], v[166:169], v[190:193], v[88:91]
	v_mfma_f32_16x16x32_bf16 v[76:79], v[158:161], v[198:201], v[76:79]
	v_mfma_f32_16x16x32_bf16 v[72:75], v[166:169], v[198:201], v[72:75]
	v_mfma_f32_16x16x32_bf16 v[116:119], v[202:205], v[170:173], v[116:119]
	v_mfma_f32_16x16x32_bf16 v[112:115], v[210:213], v[170:173], v[112:115]
	v_mfma_f32_16x16x32_bf16 v[100:103], v[202:205], v[178:181], v[100:103]
	v_mfma_f32_16x16x32_bf16 v[96:99], v[210:213], v[178:181], v[96:99]
	v_mfma_f32_16x16x32_bf16 v[84:87], v[202:205], v[186:189], v[84:87]
	v_mfma_f32_16x16x32_bf16 v[80:83], v[210:213], v[186:189], v[80:83]
	v_mfma_f32_16x16x32_bf16 v[68:71], v[202:205], v[194:197], v[68:71]
	v_mfma_f32_16x16x32_bf16 v[64:67], v[210:213], v[194:197], v[64:67]
	v_mfma_f32_16x16x32_bf16 v[116:119], v[206:209], v[174:177], v[116:119]
	v_mfma_f32_16x16x32_bf16 v[112:115], v[214:217], v[174:177], v[112:115]
	v_mfma_f32_16x16x32_bf16 v[100:103], v[206:209], v[182:185], v[100:103]
	v_mfma_f32_16x16x32_bf16 v[96:99], v[214:217], v[182:185], v[96:99]
	v_mfma_f32_16x16x32_bf16 v[84:87], v[206:209], v[190:193], v[84:87]
	v_mfma_f32_16x16x32_bf16 v[80:83], v[214:217], v[190:193], v[80:83]
	v_mfma_f32_16x16x32_bf16 v[68:71], v[206:209], v[198:201], v[68:71]
	v_mfma_f32_16x16x32_bf16 v[64:67], v[214:217], v[198:201], v[64:67]
	s_barrier
; #define PG8_STAGE(bufoff, gbase, voff) do { _Pragma("unroll") for (int _i = 0; _i < 2; ++_i) \
;         __builtin_amdgcn_global_load_lds((const unsigned*)((const char*)(gbase) + (voff)[_i]), (LAS unsigned*)(lds + (bufoff) + ldsw + _i * 8192), 16, 0, 0); } while (0)
; #define PG8_LDA(dst, b, h) do { _Pragma("unroll") for (int m = 0; m < 4; ++m) _Pragma("unroll") for (int k = 0; k < 2; ++k) dst[m][k] = *(const LAS bf16x8*)(lds + PG8_SA(b, h) + aoff + m * 2048 + k * 1024); } while (0)
; #define PG8_LDB(dst, b, h) do { _Pragma("unroll") for (int n = 0; n < 2; ++n) _Pragma("unroll") for (int k = 0; k < 2; ++k) dst[n][k] = *(const LAS bf16x8*)(lds + PG8_SB(b, h) + boff + n * 2048 + k * 1024); } while (0)
; #define PG8_MMA(ai, bj, At, Bt) do { __builtin_amdgcn_s_setprio(1); _Pragma("unroll") for (int m = 0; m < 4; ++m) _Pragma("unroll") for (int n = 0; n < 2; ++n) _Pragma("unroll") for (int k = 0; k < 2; ++k) \
;         acc[ai][bj][m][n] = __builtin_amdgcn_mfma_f32_16x16x32_bf16(Bt[n][k], At[m][k], acc[ai][bj][m][n], 0, 0, 0); __builtin_amdgcn_s_setprio(0); } while (0)
; #define PG8_WAIT_V(n) asm volatile("s_waitcnt vmcnt(" #n ")" ::: "memory")
; #define PG8_WAIT_L(n) asm volatile("s_waitcnt lgkmcnt(" #n ")" ::: "memory")
; #define PG8_BAR __builtin_amdgcn_s_barrier()
; #define PG8_SCHED __builtin_amdgcn_sched_barrier(0)
; template <class Epi>
; __device__ __forceinline__ void gemm_phase(LAS unsigned char* lds, const Gemm g, const StaticOrder& S, const Epi& E) {
;     ...
;             PG8_LDB(B1, 1, 1); PG8_STAGE(PG8_SB(1, 0), b3, voffB);
;             PG8_BAR; PG8_WAIT_L(0); PG8_MMA(0, 1, At, B1); PG8_BAR;
;             PG8_LDA(At, 1, 1); PG8_STAGE(PG8_SA(1, 0), a3, voffA);
;             PG8_BAR; PG8_WAIT_L(0); PG8_MMA(1, 0, At, B0); PG8_BAR; PG8_SCHED;
;             PG8_STAGE(PG8_SB(1, 1), b3 + hstepB, voffB);
;             PG8_WAIT_V(6); PG8_BAR; PG8_MMA(1, 1, At, B1); PG8_BAR;
	ds_read_b128 v[170:173], v155 offset:49152
	ds_read_b128 v[174:177], v155 offset:50176
	ds_read_b128 v[178:181], v155 offset:51200
	ds_read_b128 v[182:185], v155 offset:52224
	ds_read_b128 v[186:189], v155 offset:53248
	ds_read_b128 v[190:193], v155 offset:54272
	ds_read_b128 v[194:197], v155 offset:55296
	ds_read_b128 v[198:201], v155 offset:56320
	s_add_i32 s55, s55, s35
	s_mov_b32 m0, s55
	v_lshl_add_u64 v[218:219], v[218:219], 0, s[28:29]
	global_load_lds_dwordx4 v[218:219], off
	s_add_i32 m0, s55, 0x2000
	v_lshl_add_u64 v[218:219], v[220:221], 0, s[28:29]
	global_load_lds_dwordx4 v[218:219], off
	s_mov_b32 m0, s73
	v_lshl_add_u64 v[218:219], v[222:223], 0, s[28:29]
	global_load_lds_dwordx4 v[218:219], off
	s_mov_b32 m0, s74
	v_lshl_add_u64 v[218:219], v[224:225], 0, s[28:29]
	global_load_lds_dwordx4 v[218:219], off
	s_add_u32 s64, s64, 0x40080
	s_addc_u32 s65, s65, 0
	s_add_i32 s55, s98, s35
	s_mov_b32 m0, s55
	v_lshl_add_u64 v[240:241], s[64:65], 0, v[132:133]
	global_load_lds_dwordx4 v[240:241], off
	s_add_i32 m0, s55, 0x2000
	v_lshl_add_u64 v[240:241], s[64:65], 0, v[136:137]
	global_load_lds_dwordx4 v[240:241], off
	s_waitcnt vmcnt(8) lgkmcnt(0)
	s_barrier
	v_mfma_f32_16x16x32_bf16 v[60:63], v[146:149], v[170:173], v[60:63]
	v_mfma_f32_16x16x32_bf16 v[56:59], v[162:165], v[170:173], v[56:59]
	v_mfma_f32_16x16x32_bf16 v[44:47], v[146:149], v[178:181], v[44:47]
	v_mfma_f32_16x16x32_bf16 v[40:43], v[162:165], v[178:181], v[40:43]
	v_mfma_f32_16x16x32_bf16 v[28:31], v[146:149], v[186:189], v[28:31]
	v_mfma_f32_16x16x32_bf16 v[24:27], v[162:165], v[186:189], v[24:27]
	v_mfma_f32_16x16x32_bf16 v[12:15], v[146:149], v[194:197], v[12:15]
	v_mfma_f32_16x16x32_bf16 v[8:11], v[162:165], v[194:197], v[8:11]
	v_mfma_f32_16x16x32_bf16 v[60:63], v[158:161], v[174:177], v[60:63]
	v_mfma_f32_16x16x32_bf16 v[56:59], v[166:169], v[174:177], v[56:59]
	v_mfma_f32_16x16x32_bf16 v[44:47], v[158:161], v[182:185], v[44:47]
	v_mfma_f32_16x16x32_bf16 v[40:43], v[166:169], v[182:185], v[40:43]
	v_mfma_f32_16x16x32_bf16 v[28:31], v[158:161], v[190:193], v[28:31]
	v_mfma_f32_16x16x32_bf16 v[24:27], v[166:169], v[190:193], v[24:27]
	v_mfma_f32_16x16x32_bf16 v[12:15], v[158:161], v[198:201], v[12:15]
	v_mfma_f32_16x16x32_bf16 v[8:11], v[166:169], v[198:201], v[8:11]
	v_mfma_f32_16x16x32_bf16 v[52:55], v[202:205], v[170:173], v[52:55]
	v_mfma_f32_16x16x32_bf16 v[48:51], v[210:213], v[170:173], v[48:51]
	v_mfma_f32_16x16x32_bf16 v[36:39], v[202:205], v[178:181], v[36:39]
	v_mfma_f32_16x16x32_bf16 v[32:35], v[210:213], v[178:181], v[32:35]
	v_mfma_f32_16x16x32_bf16 v[20:23], v[202:205], v[186:189], v[20:23]
	v_mfma_f32_16x16x32_bf16 v[16:19], v[210:213], v[186:189], v[16:19]
	v_mfma_f32_16x16x32_bf16 v[4:7], v[202:205], v[194:197], v[4:7]
	v_mfma_f32_16x16x32_bf16 v[0:3], v[210:213], v[194:197], v[0:3]
	v_mfma_f32_16x16x32_bf16 v[52:55], v[206:209], v[174:177], v[52:55]
	v_mfma_f32_16x16x32_bf16 v[48:51], v[214:217], v[174:177], v[48:51]
	v_mfma_f32_16x16x32_bf16 v[36:39], v[206:209], v[182:185], v[36:39]
	v_mfma_f32_16x16x32_bf16 v[32:35], v[214:217], v[182:185], v[32:35]
	v_mfma_f32_16x16x32_bf16 v[20:23], v[206:209], v[190:193], v[20:23]
	v_mfma_f32_16x16x32_bf16 v[16:19], v[214:217], v[190:193], v[16:19]
	v_mfma_f32_16x16x32_bf16 v[4:7], v[206:209], v[198:201], v[4:7]
	v_mfma_f32_16x16x32_bf16 v[0:3], v[214:217], v[198:201], v[0:3]
	s_add_i32 s33, s33, 2
	s_add_u32 s62, s62, 0x100
	s_addc_u32 s63, s63, 0
	s_add_u32 s9, s9, 0x100
	s_addc_u32 s31, s31, 0
	s_cmp_gt_u32 s33, 13
	s_barrier

; #define PG8_STAGE(bufoff, gbase, voff) do { _Pragma("unroll") for (int _i = 0; _i < 2; ++_i) \
;         __builtin_amdgcn_global_load_lds((const unsigned*)((const char*)(gbase) + (voff)[_i]), (LAS unsigned*)(lds + (bufoff) + ldsw + _i * 8192), 16, 0, 0); } while (0)
; #define PG8_WAIT_V(n) asm volatile("s_waitcnt vmcnt(" #n ")" ::: "memory")
; #define PG8_BAR __builtin_amdgcn_s_barrier()
; template <class Epi>
; __device__ __forceinline__ void gemm_phase(LAS unsigned char* lds, const Gemm g, const StaticOrder& S, const Epi& E) {
;     ...
;     for (int i = 0; i < 2; ++i) { int R, C; stage_rc(tid * 16 + i * 8192, R, C); const int Rb = Epi::PERM ? ((R & ~31) + perm32(R & 31)) : R;
;         voffA[i] = (unsigned)(R * lda + C) * 2u; voffB[i] = (unsigned)(Rb * K + C) * 2u; }
;     const size_t kstep = (size_t)(BK * 2);
;     const size_t hstepA = (size_t)HALF * lda * 2, hstepB = (size_t)HALF * K * 2;
;     const size_t tstepA = 2 * hstepA, tstepB = 2 * hstepB;
;     const unsigned ldsw = (unsigned)wid * 1024u;
;     const int aoff = lds_byte(wr * 64 + fr, fq * 8), boff = lds_byte(wc * 32 + fr, fq * 8);
;     ...
;     Unit cur, nxt; int ui = 0;
;     if (!S.next(0, cur)) return;
;     f32x4 acc[2][2][4][2];
; #pragma unroll
;     for (int a = 0; a < 2; ++a)
; #pragma unroll
;         for (int b = 0; b < 2; ++b)
; #pragma unroll
;             for (int m = 0; m < 4; ++m)
; #pragma unroll
;                 for (int n = 0; n < 2; ++n) acc[a][b][m][n] = (f32x4){0.f, 0.f, 0.f, 0.f};
;     bf16x8 At[4][2], B0[2][2], B1[2][2];
;     const char* cA = (const char*)g.A + (size_t)cur.pm * tstepA + (size_t)cur.kt0 * kstep; const char* cB = (const char*)g.Bt + (size_t)cur.pn * tstepB + (size_t)cur.kt0 * kstep;
;     PG8_STAGE(PG8_SB(0, 0), cB, voffB); PG8_STAGE(PG8_SA(0, 0), cA, voffA); PG8_STAGE(PG8_SB(0, 1), cB + hstepB, voffB); PG8_STAGE(PG8_SA(0, 1), cA + hstepA, voffA);
;     if (wr == 1) PG8_BAR;
;     PG8_WAIT_V(4); PG8_BAR;
;     PG8_STAGE(PG8_SB(1, 0), cB + kstep, voffB); PG8_STAGE(PG8_SA(1, 0), cA + kstep, voffA); PG8_STAGE(PG8_SB(1, 1), cB + hstepB + kstep, voffB);
;     PG8_WAIT_V(6); PG8_BAR;
.LBB0_439:
	s_lshl_b32 s0, s12, 5
	s_mov_b64 s[12:13], 0x80
	s_and_b32 s31, s0, 0x60
	s_add_i32 m0, s35, 0x18000
	v_lshl_add_u64 v[6:7], v[6:7], 0, s[12:13]
	s_lshl_b32 s21, s20, 13
	s_lshl_b32 s56, s31, 7
	s_waitcnt vmcnt(0)
	s_barrier
	global_load_lds_dwordx4 v[6:7], off
	v_lshl_add_u64 v[4:5], v[4:5], 0, s[12:13]
	s_add_i32 m0, s35, 0x1a000
	s_add_i32 s73, s35, 0x8000
	s_add_i32 s74, s35, 0xa000
	global_load_lds_dwordx4 v[4:5], off
	v_lshl_add_u64 v[0:1], v[0:1], 0, s[12:13]
	s_mov_b32 m0, s73
	s_add_u32 s0, s66, 0x40080
	global_load_lds_dwordx4 v[0:1], off
	v_lshl_add_u64 v[0:1], v[2:3], 0, s[12:13]
	s_mov_b32 m0, s74
	s_addc_u32 s1, s67, 0
	global_load_lds_dwordx4 v[0:1], off
	s_add_i32 m0, s35, 0x1c000
	v_lshl_add_u64 v[0:1], s[0:1], 0, v[132:133]
	global_load_lds_dwordx4 v[0:1], off
	v_lshl_add_u64 v[0:1], s[0:1], 0, v[136:137]
	s_add_i32 m0, s35, 0x1e000
	v_lshlrev_b32_e32 v2, 2, v129
	global_load_lds_dwordx4 v[0:1], off
	v_and_b32_e32 v0, 15, v129
	v_lshlrev_b32_e32 v1, 1, v11
	v_lshlrev_b32_e32 v3, 6, v129
	s_movk_i32 s0, 0x3c0
	v_lshl_or_b32 v155, s20, 6, v0
	v_lshl_or_b32 v0, v0, 6, v1
	v_and_b32_e32 v2, 32, v2
	v_and_or_b32 v1, v3, s0, v1
	v_bitop3_b32 v156, s56, v1, v2 bitop3:0xf6
	v_lshlrev_b32_e32 v1, 8, v129
	v_bitop3_b32 v0, v0, s21, v2 bitop3:0xde
	v_and_b32_e32 v1, 0x38000, v1
	v_lshlrev_b32_e32 v2, 11, v10
	v_or3_b32 v1, v8, v1, v2
	v_add_u32_e32 v138, v1, v9
	v_lshlrev_b32_e32 v1, 4, v12
	s_waitcnt vmcnt(6)
	v_and_b32_e32 v1, 0x78000, v1
	v_or3_b32 v1, v8, v1, v2
	s_add_i32 s78, 0, 0x10000
	s_add_i32 s79, 0, 0x14000
	s_ashr_i32 s75, s14, 31
	s_mov_b32 s76, s14
	s_ashr_i32 s77, s2, 31
	v_or_b32_e32 v157, s31, v11
	v_mov_b32_e32 v139, v133
	v_add_u32_e32 v140, v1, v9
	v_mov_b32_e32 v141, v133
	v_mov_b64_e32 v[142:143], 0xff
	v_add_u32_e32 v158, s78, v156
	v_add_u32_e32 v159, 0, v0
	v_add_u32_e32 v160, s79, v156
	s_mov_b32 s80, 0
	s_barrier
	s_mov_b32 s99, 0
	s_branch .LBB0_442

; #define PG8_STAGE(bufoff, gbase, voff) do { _Pragma("unroll") for (int _i = 0; _i < 2; ++_i) \
;         __builtin_amdgcn_global_load_lds((const unsigned*)((const char*)(gbase) + (voff)[_i]), (LAS unsigned*)(lds + (bufoff) + ldsw + _i * 8192), 16, 0, 0); } while (0)
; #define PG8_LDA(dst, b, h) do { _Pragma("unroll") for (int m = 0; m < 4; ++m) _Pragma("unroll") for (int k = 0; k < 2; ++k) dst[m][k] = *(const LAS bf16x8*)(lds + PG8_SA(b, h) + aoff + m * 2048 + k * 1024); } while (0)
; #define PG8_LDB(dst, b, h) do { _Pragma("unroll") for (int n = 0; n < 2; ++n) _Pragma("unroll") for (int k = 0; k < 2; ++k) dst[n][k] = *(const LAS bf16x8*)(lds + PG8_SB(b, h) + boff + n * 2048 + k * 1024); } while (0)
; #define PG8_MMA(ai, bj, At, Bt) do { __builtin_amdgcn_s_setprio(1); _Pragma("unroll") for (int m = 0; m < 4; ++m) _Pragma("unroll") for (int n = 0; n < 2; ++n) _Pragma("unroll") for (int k = 0; k < 2; ++k) \
;         acc[ai][bj][m][n] = __builtin_amdgcn_mfma_f32_16x16x32_bf16(Bt[n][k], At[m][k], acc[ai][bj][m][n], 0, 0, 0); __builtin_amdgcn_s_setprio(0); } while (0)
; #define PG8_WAIT_L(n) asm volatile("s_waitcnt lgkmcnt(" #n ")" ::: "memory")
; #define PG8_BAR __builtin_amdgcn_s_barrier()
; #define PG8_SCHED __builtin_amdgcn_sched_barrier(0)
; template <class Epi>
; __device__ __forceinline__ void gemm_phase(LAS unsigned char* lds, const Gemm g, const StaticOrder& S, const Epi& E) {
;     ...
;         const bool has_next = S.next(ui + 1, nxt);
;         const char* nA = has_next ? (const char*)g.A + (size_t)nxt.pm * tstepA + (size_t)nxt.kt0 * kstep : cA; const char* nB = has_next ? (const char*)g.Bt + (size_t)nxt.pn * tstepB + (size_t)nxt.kt0 * kstep : cB;
;         const int nt = cur.nkt;
;         for (int t = 0; t < nt; t += 2) {
;             const bool last = (t == nt - 2);
;             const char* a1 = cA + (size_t)(t + 1) * kstep;
;             const char* a2 = last ? nA : cA + (size_t)(t + 2) * kstep; const char* b2 = last ? nB : cB + (size_t)(t + 2) * kstep;
;             const char* a3 = a2 + kstep; const char* b3 = b2 + kstep;
;             PG8_LDB(B0, 0, 0); PG8_SCHED; PG8_LDA(At, 0, 0); PG8_STAGE(PG8_SA(1, 1), a1 + hstepA, voffA);
;             PG8_WAIT_L(8); PG8_BAR; PG8_WAIT_L(0); PG8_MMA(0, 0, At, B0); PG8_BAR; PG8_SCHED;
.LBB0_455:
	s_add_i32 s21, s84, -2
	s_add_u32 s64, s64, 0x40080
	s_addc_u32 s65, s65, 0
	s_add_u32 s31, s66, 0x100
	s_addc_u32 s57, s67, 0
	s_mov_b32 s59, 0
	s_add_i32 s85, s59, 2
	s_add_u32 s66, s64, 0xfffc0080
	s_addc_u32 s67, s65, -1
	s_cmp_eq_u32 s21, s59
	s_cselect_b32 s69, s63, s67
	s_cselect_b32 s68, s62, s66
	s_cselect_b32 s67, s1, s57
	s_cselect_b32 s66, s0, s31
	ds_read_b128 v[144:147], v158
	ds_read_b128 v[148:151], v158 offset:1024
	ds_read_b128 v[162:165], v158 offset:2048
	ds_read_b128 v[166:169], v158 offset:3072
	ds_read_b128 v[170:173], v159
	ds_read_b128 v[174:177], v159 offset:1024
	ds_read_b128 v[178:181], v159 offset:2048
	ds_read_b128 v[182:185], v159 offset:3072
	ds_read_b128 v[186:189], v159 offset:4096
	ds_read_b128 v[190:193], v159 offset:5120
	ds_read_b128 v[194:197], v159 offset:6144
	ds_read_b128 v[198:201], v159 offset:7168
	ds_read_b128 v[202:205], v160
	ds_read_b128 v[206:209], v160 offset:1024
	ds_read_b128 v[210:213], v160 offset:2048
	ds_read_b128 v[214:217], v160 offset:3072
	s_add_i32 m0, s35, 0xc000
	v_lshl_add_u64 v[152:153], s[64:65], 0, v[138:139]
	global_load_lds_dwordx4 v[152:153], off
	s_add_i32 m0, s35, 0xe000
	v_lshl_add_u64 v[152:153], s[64:65], 0, v[140:141]
	global_load_lds_dwordx4 v[152:153], off
	s_cmp_eq_u32 s99, 0
	s_cbranch_scc1 .Lrw1_0s
	s_waitcnt vmcnt(24) lgkmcnt(0)
	s_branch .Lrw1_0d

; #define PG8_STAGE(bufoff, gbase, voff) do { _Pragma("unroll") for (int _i = 0; _i < 2; ++_i) \
;         __builtin_amdgcn_global_load_lds((const unsigned*)((const char*)(gbase) + (voff)[_i]), (LAS unsigned*)(lds + (bufoff) + ldsw + _i * 8192), 16, 0, 0); } while (0)
; #define PG8_LDA(dst, b, h) do { _Pragma("unroll") for (int m = 0; m < 4; ++m) _Pragma("unroll") for (int k = 0; k < 2; ++k) dst[m][k] = *(const LAS bf16x8*)(lds + PG8_SA(b, h) + aoff + m * 2048 + k * 1024); } while (0)
; #define PG8_LDB(dst, b, h) do { _Pragma("unroll") for (int n = 0; n < 2; ++n) _Pragma("unroll") for (int k = 0; k < 2; ++k) dst[n][k] = *(const LAS bf16x8*)(lds + PG8_SB(b, h) + boff + n * 2048 + k * 1024); } while (0)
; #define PG8_MMA(ai, bj, At, Bt) do { __builtin_amdgcn_s_setprio(1); _Pragma("unroll") for (int m = 0; m < 4; ++m) _Pragma("unroll") for (int n = 0; n < 2; ++n) _Pragma("unroll") for (int k = 0; k < 2; ++k) \
;         acc[ai][bj][m][n] = __builtin_amdgcn_mfma_f32_16x16x32_bf16(Bt[n][k], At[m][k], acc[ai][bj][m][n], 0, 0, 0); __builtin_amdgcn_s_setprio(0); } while (0)
; #define PG8_WAIT_L(n) asm volatile("s_waitcnt lgkmcnt(" #n ")" ::: "memory")
; #define PG8_BAR __builtin_amdgcn_s_barrier()
; #define PG8_SCHED __builtin_amdgcn_sched_barrier(0)
; template <class Epi>
; __device__ __forceinline__ void gemm_phase(LAS unsigned char* lds, const Gemm g, const StaticOrder& S, const Epi& E) {
;     ...
;             PG8_LDB(B0, 0, 0); PG8_SCHED; PG8_LDA(At, 0, 0); PG8_STAGE(PG8_SA(1, 1), a1 + hstepA, voffA);
;             PG8_WAIT_L(8); PG8_BAR; PG8_WAIT_L(0); PG8_MMA(0, 0, At, B0); PG8_BAR; PG8_SCHED;
;             PG8_LDB(B1, 0, 1); PG8_STAGE(PG8_SB(0, 0), b2, voffB);
;             PG8_BAR; PG8_WAIT_L(0); PG8_MMA(0, 1, At, B1); PG8_BAR;
;             PG8_LDA(At, 0, 1); PG8_STAGE(PG8_SA(0, 0), a2, voffA);
;             PG8_BAR; PG8_WAIT_L(0); PG8_MMA(1, 0, At, B0); PG8_BAR; PG8_SCHED;
.Lrw1_0d:
	s_barrier
	v_mfma_f32_16x16x32_bf16 v[124:127], v[144:147], v[170:173], 0
	v_mfma_f32_16x16x32_bf16 v[120:123], v[162:165], v[170:173], 0
	v_mfma_f32_16x16x32_bf16 v[116:119], v[144:147], v[178:181], 0
	v_mfma_f32_16x16x32_bf16 v[108:111], v[162:165], v[178:181], 0
	v_mfma_f32_16x16x32_bf16 v[100:103], v[144:147], v[186:189], 0
	v_mfma_f32_16x16x32_bf16 v[92:95], v[162:165], v[186:189], 0
	v_mfma_f32_16x16x32_bf16 v[84:87], v[144:147], v[194:197], 0
	v_mfma_f32_16x16x32_bf16 v[76:79], v[162:165], v[194:197], 0
	v_mfma_f32_16x16x32_bf16 v[124:127], v[148:151], v[174:177], v[124:127]
	v_mfma_f32_16x16x32_bf16 v[120:123], v[166:169], v[174:177], v[120:123]
	v_mfma_f32_16x16x32_bf16 v[116:119], v[148:151], v[182:185], v[116:119]
	v_mfma_f32_16x16x32_bf16 v[108:111], v[166:169], v[182:185], v[108:111]
	v_mfma_f32_16x16x32_bf16 v[100:103], v[148:151], v[190:193], v[100:103]
	v_mfma_f32_16x16x32_bf16 v[92:95], v[166:169], v[190:193], v[92:95]
	v_mfma_f32_16x16x32_bf16 v[84:87], v[148:151], v[198:201], v[84:87]
	v_mfma_f32_16x16x32_bf16 v[76:79], v[166:169], v[198:201], v[76:79]
	v_mfma_f32_16x16x32_bf16 v[112:115], v[202:205], v[170:173], 0
	v_mfma_f32_16x16x32_bf16 v[104:107], v[210:213], v[170:173], 0
	v_mfma_f32_16x16x32_bf16 v[96:99], v[202:205], v[178:181], 0
	v_mfma_f32_16x16x32_bf16 v[88:91], v[210:213], v[178:181], 0
	v_mfma_f32_16x16x32_bf16 v[80:83], v[202:205], v[186:189], 0
	v_mfma_f32_16x16x32_bf16 v[72:75], v[210:213], v[186:189], 0
	v_mfma_f32_16x16x32_bf16 v[68:71], v[202:205], v[194:197], 0
	v_mfma_f32_16x16x32_bf16 v[64:67], v[210:213], v[194:197], 0
	v_mfma_f32_16x16x32_bf16 v[112:115], v[206:209], v[174:177], v[112:115]
	v_mfma_f32_16x16x32_bf16 v[104:107], v[214:217], v[174:177], v[104:107]
	v_mfma_f32_16x16x32_bf16 v[96:99], v[206:209], v[182:185], v[96:99]
	v_mfma_f32_16x16x32_bf16 v[88:91], v[214:217], v[182:185], v[88:91]
	v_mfma_f32_16x16x32_bf16 v[80:83], v[206:209], v[190:193], v[80:83]
	v_mfma_f32_16x16x32_bf16 v[72:75], v[214:217], v[190:193], v[72:75]
	v_mfma_f32_16x16x32_bf16 v[68:71], v[206:209], v[198:201], v[68:71]
	v_mfma_f32_16x16x32_bf16 v[64:67], v[214:217], v[198:201], v[64:67]
	s_barrier
	ds_read_b128 v[170:173], v159 offset:16384
	ds_read_b128 v[174:177], v159 offset:17408
	ds_read_b128 v[178:181], v159 offset:18432
	ds_read_b128 v[182:185], v159 offset:19456
	ds_read_b128 v[186:189], v159 offset:20480
	ds_read_b128 v[190:193], v159 offset:21504
	ds_read_b128 v[194:197], v159 offset:22528
	ds_read_b128 v[198:201], v159 offset:23552
	s_add_i32 s59, s78, s33
	s_mov_b32 m0, s59
	v_lshl_add_u64 v[152:153], s[66:67], 0, v[132:133]
	global_load_lds_dwordx4 v[152:153], off
	s_add_i32 m0, s59, 0x2000
	v_lshl_add_u64 v[218:219], s[66:67], 0, v[136:137]
	global_load_lds_dwordx4 v[218:219], off
	s_mov_b32 m0, s35
	v_lshl_add_u64 v[220:221], s[68:69], 0, v[130:131]
	global_load_lds_dwordx4 v[220:221], off
	s_mov_b32 m0, s70
	v_lshl_add_u64 v[222:223], s[68:69], 0, v[134:135]
	global_load_lds_dwordx4 v[222:223], off
	s_add_u32 s86, s66, 0x40000
	s_addc_u32 s87, s67, 0
	s_add_i32 s59, s79, s33
	s_mov_b32 m0, s59
	v_lshl_add_u64 v[240:241], s[86:87], 0, v[132:133]
	global_load_lds_dwordx4 v[240:241], off
	s_add_i32 m0, s59, 0x2000
	v_lshl_add_u64 v[240:241], s[86:87], 0, v[136:137]
	global_load_lds_dwordx4 v[240:241], off
	s_cmp_eq_u32 s99, 0
	s_cbranch_scc1 .Lrw1_1s
	s_waitcnt vmcnt(24) lgkmcnt(0)
	s_branch .Lrw1_1d

; #define PG8_STAGE(bufoff, gbase, voff) do { _Pragma("unroll") for (int _i = 0; _i < 2; ++_i) \
;         __builtin_amdgcn_global_load_lds((const unsigned*)((const char*)(gbase) + (voff)[_i]), (LAS unsigned*)(lds + (bufoff) + ldsw + _i * 8192), 16, 0, 0); } while (0)
; #define PG8_LDA(dst, b, h) do { _Pragma("unroll") for (int m = 0; m < 4; ++m) _Pragma("unroll") for (int k = 0; k < 2; ++k) dst[m][k] = *(const LAS bf16x8*)(lds + PG8_SA(b, h) + aoff + m * 2048 + k * 1024); } while (0)
; #define PG8_LDB(dst, b, h) do { _Pragma("unroll") for (int n = 0; n < 2; ++n) _Pragma("unroll") for (int k = 0; k < 2; ++k) dst[n][k] = *(const LAS bf16x8*)(lds + PG8_SB(b, h) + boff + n * 2048 + k * 1024); } while (0)
; #define PG8_MMA(ai, bj, At, Bt) do { __builtin_amdgcn_s_setprio(1); _Pragma("unroll") for (int m = 0; m < 4; ++m) _Pragma("unroll") for (int n = 0; n < 2; ++n) _Pragma("unroll") for (int k = 0; k < 2; ++k) \
;         acc[ai][bj][m][n] = __builtin_amdgcn_mfma_f32_16x16x32_bf16(Bt[n][k], At[m][k], acc[ai][bj][m][n], 0, 0, 0); __builtin_amdgcn_s_setprio(0); } while (0)
; #define PG8_WAIT_V(n) asm volatile("s_waitcnt vmcnt(" #n ")" ::: "memory")
; #define PG8_WAIT_L(n) asm volatile("s_waitcnt lgkmcnt(" #n ")" ::: "memory")
; #define PG8_BAR __builtin_amdgcn_s_barrier()
; #define PG8_SCHED __builtin_amdgcn_sched_barrier(0)
; template <class Epi>
; __device__ __forceinline__ void gemm_phase(LAS unsigned char* lds, const Gemm g, const StaticOrder& S, const Epi& E) {
;     ...
;             PG8_BAR; PG8_WAIT_L(0); PG8_MMA(0, 1, At, B1); PG8_BAR;
;             PG8_LDA(At, 0, 1); PG8_STAGE(PG8_SA(0, 0), a2, voffA);
;             PG8_BAR; PG8_WAIT_L(0); PG8_MMA(1, 0, At, B0); PG8_BAR; PG8_SCHED;
;             PG8_STAGE(PG8_SB(0, 1), b2 + hstepB, voffB);
;             PG8_WAIT_V(6); PG8_BAR; PG8_MMA(1, 1, At, B1); PG8_BAR;
;             PG8_LDB(B0, 1, 0); PG8_SCHED; PG8_LDA(At, 1, 0); PG8_STAGE(PG8_SA(0, 1), a2 + hstepA, voffA);
;             PG8_WAIT_L(8); PG8_BAR; PG8_WAIT_L(0); PG8_MMA(0, 0, At, B0); PG8_BAR; PG8_SCHED;
.Lrw1_1d:
	s_mov_b32 s99, 1
	s_barrier
	v_mfma_f32_16x16x32_bf16 v[60:63], v[144:147], v[170:173], 0
	v_mfma_f32_16x16x32_bf16 v[56:59], v[162:165], v[170:173], 0
	v_mfma_f32_16x16x32_bf16 v[52:55], v[144:147], v[178:181], 0
	v_mfma_f32_16x16x32_bf16 v[44:47], v[162:165], v[178:181], 0
	v_mfma_f32_16x16x32_bf16 v[36:39], v[144:147], v[186:189], 0
	v_mfma_f32_16x16x32_bf16 v[28:31], v[162:165], v[186:189], 0
	v_mfma_f32_16x16x32_bf16 v[20:23], v[144:147], v[194:197], 0
	v_mfma_f32_16x16x32_bf16 v[12:15], v[162:165], v[194:197], 0
	v_mfma_f32_16x16x32_bf16 v[60:63], v[148:151], v[174:177], v[60:63]
	v_mfma_f32_16x16x32_bf16 v[56:59], v[166:169], v[174:177], v[56:59]
	v_mfma_f32_16x16x32_bf16 v[52:55], v[148:151], v[182:185], v[52:55]
	v_mfma_f32_16x16x32_bf16 v[44:47], v[166:169], v[182:185], v[44:47]
	v_mfma_f32_16x16x32_bf16 v[36:39], v[148:151], v[190:193], v[36:39]
	v_mfma_f32_16x16x32_bf16 v[28:31], v[166:169], v[190:193], v[28:31]
	v_mfma_f32_16x16x32_bf16 v[20:23], v[148:151], v[198:201], v[20:23]
	v_mfma_f32_16x16x32_bf16 v[12:15], v[166:169], v[198:201], v[12:15]
	v_mfma_f32_16x16x32_bf16 v[48:51], v[202:205], v[170:173], 0
	v_mfma_f32_16x16x32_bf16 v[40:43], v[210:213], v[170:173], 0
	v_mfma_f32_16x16x32_bf16 v[32:35], v[202:205], v[178:181], 0
	v_mfma_f32_16x16x32_bf16 v[24:27], v[210:213], v[178:181], 0
	v_mfma_f32_16x16x32_bf16 v[16:19], v[202:205], v[186:189], 0
	v_mfma_f32_16x16x32_bf16 v[8:11], v[210:213], v[186:189], 0
	v_mfma_f32_16x16x32_bf16 v[4:7], v[202:205], v[194:197], 0
	v_mfma_f32_16x16x32_bf16 v[0:3], v[210:213], v[194:197], 0
	v_mfma_f32_16x16x32_bf16 v[48:51], v[206:209], v[174:177], v[48:51]
	v_mfma_f32_16x16x32_bf16 v[40:43], v[214:217], v[174:177], v[40:43]
	v_mfma_f32_16x16x32_bf16 v[32:35], v[206:209], v[182:185], v[32:35]
	v_mfma_f32_16x16x32_bf16 v[24:27], v[214:217], v[182:185], v[24:27]
	v_mfma_f32_16x16x32_bf16 v[16:19], v[206:209], v[190:193], v[16:19]
	v_mfma_f32_16x16x32_bf16 v[8:11], v[214:217], v[190:193], v[8:11]
	v_mfma_f32_16x16x32_bf16 v[4:7], v[206:209], v[198:201], v[4:7]
	v_mfma_f32_16x16x32_bf16 v[0:3], v[214:217], v[198:201], v[0:3]
	s_barrier
	s_add_i32 s59, 0, 0x18000
	v_add_u32_e32 v161, s59, v156
	ds_read_b128 v[144:147], v161
	ds_read_b128 v[148:151], v161 offset:1024
	ds_read_b128 v[162:165], v161 offset:2048
	ds_read_b128 v[166:169], v161 offset:3072
	ds_read_b128 v[170:173], v159 offset:32768
	ds_read_b128 v[174:177], v159 offset:33792
	ds_read_b128 v[178:181], v159 offset:34816
	ds_read_b128 v[182:185], v159 offset:35840
	ds_read_b128 v[186:189], v159 offset:36864
	ds_read_b128 v[190:193], v159 offset:37888
	ds_read_b128 v[194:197], v159 offset:38912
	ds_read_b128 v[198:201], v159 offset:39936
	s_add_i32 s98, 0, 0x1c000
	v_add_u32_e32 v246, s98, v156
	ds_read_b128 v[202:205], v246
	ds_read_b128 v[206:209], v246 offset:1024
	ds_read_b128 v[210:213], v246 offset:2048
	ds_read_b128 v[214:217], v246 offset:3072
	s_add_u32 s68, s68, 0x40000
	s_addc_u32 s69, s69, 0
	s_mov_b32 m0, s71
	v_lshl_add_u64 v[244:245], s[68:69], 0, v[130:131]
	global_load_lds_dwordx4 v[244:245], off
	s_mov_b32 m0, s72
	v_lshl_add_u64 v[244:245], s[68:69], 0, v[134:135]
	global_load_lds_dwordx4 v[244:245], off
	s_waitcnt vmcnt(8) lgkmcnt(0)
	s_barrier
	v_mfma_f32_16x16x32_bf16 v[124:127], v[144:147], v[170:173], v[124:127]
	v_mfma_f32_16x16x32_bf16 v[120:123], v[162:165], v[170:173], v[120:123]
	v_mfma_f32_16x16x32_bf16 v[116:119], v[144:147], v[178:181], v[116:119]
	v_mfma_f32_16x16x32_bf16 v[108:111], v[162:165], v[178:181], v[108:111]
	v_mfma_f32_16x16x32_bf16 v[100:103], v[144:147], v[186:189], v[100:103]
	v_mfma_f32_16x16x32_bf16 v[92:95], v[162:165], v[186:189], v[92:95]
	v_mfma_f32_16x16x32_bf16 v[84:87], v[144:147], v[194:197], v[84:87]
	v_mfma_f32_16x16x32_bf16 v[76:79], v[162:165], v[194:197], v[76:79]
	v_mfma_f32_16x16x32_bf16 v[124:127], v[148:151], v[174:177], v[124:127]
	v_mfma_f32_16x16x32_bf16 v[120:123], v[166:169], v[174:177], v[120:123]
	v_mfma_f32_16x16x32_bf16 v[116:119], v[148:151], v[182:185], v[116:119]
	v_mfma_f32_16x16x32_bf16 v[108:111], v[166:169], v[182:185], v[108:111]
	v_mfma_f32_16x16x32_bf16 v[100:103], v[148:151], v[190:193], v[100:103]
	v_mfma_f32_16x16x32_bf16 v[92:95], v[166:169], v[190:193], v[92:95]
	v_mfma_f32_16x16x32_bf16 v[84:87], v[148:151], v[198:201], v[84:87]
	v_mfma_f32_16x16x32_bf16 v[76:79], v[166:169], v[198:201], v[76:79]
	v_mfma_f32_16x16x32_bf16 v[112:115], v[202:205], v[170:173], v[112:115]
	v_mfma_f32_16x16x32_bf16 v[104:107], v[210:213], v[170:173], v[104:107]
	v_mfma_f32_16x16x32_bf16 v[96:99], v[202:205], v[178:181], v[96:99]
	v_mfma_f32_16x16x32_bf16 v[88:91], v[210:213], v[178:181], v[88:91]
	v_mfma_f32_16x16x32_bf16 v[80:83], v[202:205], v[186:189], v[80:83]
	v_mfma_f32_16x16x32_bf16 v[72:75], v[210:213], v[186:189], v[72:75]
	v_mfma_f32_16x16x32_bf16 v[68:71], v[202:205], v[194:197], v[68:71]
	v_mfma_f32_16x16x32_bf16 v[64:67], v[210:213], v[194:197], v[64:67]
	v_mfma_f32_16x16x32_bf16 v[112:115], v[206:209], v[174:177], v[112:115]
	v_mfma_f32_16x16x32_bf16 v[104:107], v[214:217], v[174:177], v[104:107]
	v_mfma_f32_16x16x32_bf16 v[96:99], v[206:209], v[182:185], v[96:99]
	v_mfma_f32_16x16x32_bf16 v[88:91], v[214:217], v[182:185], v[88:91]
	v_mfma_f32_16x16x32_bf16 v[80:83], v[206:209], v[190:193], v[80:83]
	v_mfma_f32_16x16x32_bf16 v[72:75], v[214:217], v[190:193], v[72:75]
	v_mfma_f32_16x16x32_bf16 v[68:71], v[206:209], v[198:201], v[68:71]
	v_mfma_f32_16x16x32_bf16 v[64:67], v[214:217], v[198:201], v[64:67]
	s_barrier
; #define PG8_STAGE(bufoff, gbase, voff) do { _Pragma("unroll") for (int _i = 0; _i < 2; ++_i) \
;         __builtin_amdgcn_global_load_lds((const unsigned*)((const char*)(gbase) + (voff)[_i]), (LAS unsigned*)(lds + (bufoff) + ldsw + _i * 8192), 16, 0, 0); } while (0)
; #define PG8_LDA(dst, b, h) do { _Pragma("unroll") for (int m = 0; m < 4; ++m) _Pragma("unroll") for (int k = 0; k < 2; ++k) dst[m][k] = *(const LAS bf16x8*)(lds + PG8_SA(b, h) + aoff + m * 2048 + k * 1024); } while (0)
; #define PG8_LDB(dst, b, h) do { _Pragma("unroll") for (int n = 0; n < 2; ++n) _Pragma("unroll") for (int k = 0; k < 2; ++k) dst[n][k] = *(const LAS bf16x8*)(lds + PG8_SB(b, h) + boff + n * 2048 + k * 1024); } while (0)
; #define PG8_MMA(ai, bj, At, Bt) do { __builtin_amdgcn_s_setprio(1); _Pragma("unroll") for (int m = 0; m < 4; ++m) _Pragma("unroll") for (int n = 0; n < 2; ++n) _Pragma("unroll") for (int k = 0; k < 2; ++k) \
;         acc[ai][bj][m][n] = __builtin_amdgcn_mfma_f32_16x16x32_bf16(Bt[n][k], At[m][k], acc[ai][bj][m][n], 0, 0, 0); __builtin_amdgcn_s_setprio(0); } while (0)
; #define PG8_WAIT_V(n) asm volatile("s_waitcnt vmcnt(" #n ")" ::: "memory")
; #define PG8_WAIT_L(n) asm volatile("s_waitcnt lgkmcnt(" #n ")" ::: "memory")
; #define PG8_BAR __builtin_amdgcn_s_barrier()
; #define PG8_SCHED __builtin_amdgcn_sched_barrier(0)
; template <class Epi>
; __device__ __forceinline__ void gemm_phase(LAS unsigned char* lds, const Gemm g, const StaticOrder& S, const Epi& E) {
;     ...
;             PG8_LDB(B1, 1, 1); PG8_STAGE(PG8_SB(1, 0), b3, voffB);
;             PG8_BAR; PG8_WAIT_L(0); PG8_MMA(0, 1, At, B1); PG8_BAR;
;             PG8_LDA(At, 1, 1); PG8_STAGE(PG8_SA(1, 0), a3, voffA);
;             PG8_BAR; PG8_WAIT_L(0); PG8_MMA(1, 0, At, B0); PG8_BAR; PG8_SCHED;
;             PG8_STAGE(PG8_SB(1, 1), b3 + hstepB, voffB);
;             PG8_WAIT_V(6); PG8_BAR; PG8_MMA(1, 1, At, B1); PG8_BAR;
	ds_read_b128 v[170:173], v159 offset:49152
	ds_read_b128 v[174:177], v159 offset:50176
	ds_read_b128 v[178:181], v159 offset:51200
	ds_read_b128 v[182:185], v159 offset:52224
	ds_read_b128 v[186:189], v159 offset:53248
	ds_read_b128 v[190:193], v159 offset:54272
	ds_read_b128 v[194:197], v159 offset:55296
	ds_read_b128 v[198:201], v159 offset:56320
	s_add_i32 s59, s59, s33
	s_mov_b32 m0, s59
	v_lshl_add_u64 v[152:153], v[152:153], 0, s[12:13]
	global_load_lds_dwordx4 v[152:153], off
	s_add_i32 m0, s59, 0x2000
	v_lshl_add_u64 v[152:153], v[218:219], 0, s[12:13]
	global_load_lds_dwordx4 v[152:153], off
	s_mov_b32 m0, s73
	v_lshl_add_u64 v[152:153], v[220:221], 0, s[12:13]
	global_load_lds_dwordx4 v[152:153], off
	s_mov_b32 m0, s74
	v_lshl_add_u64 v[152:153], v[222:223], 0, s[12:13]
	global_load_lds_dwordx4 v[152:153], off
	s_add_u32 s66, s66, 0x40080
	s_addc_u32 s67, s67, 0
	s_add_i32 s59, s98, s33
	s_mov_b32 m0, s59
	v_lshl_add_u64 v[240:241], s[66:67], 0, v[132:133]
	global_load_lds_dwordx4 v[240:241], off
	s_add_i32 m0, s59, 0x2000
	v_lshl_add_u64 v[240:241], s[66:67], 0, v[136:137]
	global_load_lds_dwordx4 v[240:241], off
	s_waitcnt vmcnt(8) lgkmcnt(0)
	s_barrier
	v_mfma_f32_16x16x32_bf16 v[60:63], v[144:147], v[170:173], v[60:63]
	v_mfma_f32_16x16x32_bf16 v[56:59], v[162:165], v[170:173], v[56:59]
	v_mfma_f32_16x16x32_bf16 v[52:55], v[144:147], v[178:181], v[52:55]
	v_mfma_f32_16x16x32_bf16 v[44:47], v[162:165], v[178:181], v[44:47]
	v_mfma_f32_16x16x32_bf16 v[36:39], v[144:147], v[186:189], v[36:39]
	v_mfma_f32_16x16x32_bf16 v[28:31], v[162:165], v[186:189], v[28:31]
	v_mfma_f32_16x16x32_bf16 v[20:23], v[144:147], v[194:197], v[20:23]
	v_mfma_f32_16x16x32_bf16 v[12:15], v[162:165], v[194:197], v[12:15]
	v_mfma_f32_16x16x32_bf16 v[60:63], v[148:151], v[174:177], v[60:63]
	v_mfma_f32_16x16x32_bf16 v[56:59], v[166:169], v[174:177], v[56:59]
	v_mfma_f32_16x16x32_bf16 v[52:55], v[148:151], v[182:185], v[52:55]
	v_mfma_f32_16x16x32_bf16 v[44:47], v[166:169], v[182:185], v[44:47]
	v_mfma_f32_16x16x32_bf16 v[36:39], v[148:151], v[190:193], v[36:39]
	v_mfma_f32_16x16x32_bf16 v[28:31], v[166:169], v[190:193], v[28:31]
	v_mfma_f32_16x16x32_bf16 v[20:23], v[148:151], v[198:201], v[20:23]
	v_mfma_f32_16x16x32_bf16 v[12:15], v[166:169], v[198:201], v[12:15]
	v_mfma_f32_16x16x32_bf16 v[48:51], v[202:205], v[170:173], v[48:51]
	v_mfma_f32_16x16x32_bf16 v[40:43], v[210:213], v[170:173], v[40:43]
	v_mfma_f32_16x16x32_bf16 v[32:35], v[202:205], v[178:181], v[32:35]
	v_mfma_f32_16x16x32_bf16 v[24:27], v[210:213], v[178:181], v[24:27]
	v_mfma_f32_16x16x32_bf16 v[16:19], v[202:205], v[186:189], v[16:19]
	v_mfma_f32_16x16x32_bf16 v[8:11], v[210:213], v[186:189], v[8:11]
	v_mfma_f32_16x16x32_bf16 v[4:7], v[202:205], v[194:197], v[4:7]
	v_mfma_f32_16x16x32_bf16 v[0:3], v[210:213], v[194:197], v[0:3]
	v_mfma_f32_16x16x32_bf16 v[48:51], v[206:209], v[174:177], v[48:51]
	v_mfma_f32_16x16x32_bf16 v[40:43], v[214:217], v[174:177], v[40:43]
	v_mfma_f32_16x16x32_bf16 v[32:35], v[206:209], v[182:185], v[32:35]
	v_mfma_f32_16x16x32_bf16 v[24:27], v[214:217], v[182:185], v[24:27]
	v_mfma_f32_16x16x32_bf16 v[16:19], v[206:209], v[190:193], v[16:19]
	v_mfma_f32_16x16x32_bf16 v[8:11], v[214:217], v[190:193], v[8:11]
	v_mfma_f32_16x16x32_bf16 v[4:7], v[206:209], v[198:201], v[4:7]
	v_mfma_f32_16x16x32_bf16 v[0:3], v[214:217], v[198:201], v[0:3]
	s_add_u32 s64, s64, 0x100
	s_addc_u32 s65, s65, 0
	s_add_u32 s31, s31, 0x100
	s_addc_u32 s57, s57, 0
	s_cmp_ge_i32 s85, s84
	s_mov_b32 s59, s85
	s_barrier

; #define PG8_STAGE(bufoff, gbase, voff) do { _Pragma("unroll") for (int _i = 0; _i < 2; ++_i) \
;         __builtin_amdgcn_global_load_lds((const unsigned*)((const char*)(gbase) + (voff)[_i]), (LAS unsigned*)(lds + (bufoff) + ldsw + _i * 8192), 16, 0, 0); } while (0)
; #define PG8_WAIT_V(n) asm volatile("s_waitcnt vmcnt(" #n ")" ::: "memory")
; #define PG8_BAR __builtin_amdgcn_s_barrier()
; template <class Epi>
; __device__ __forceinline__ void gemm_phase(LAS unsigned char* lds, const Gemm g, const StaticOrder& S, const Epi& E) {
;     ...
;     for (int i = 0; i < 2; ++i) { int R, C; stage_rc(tid * 16 + i * 8192, R, C); const int Rb = Epi::PERM ? ((R & ~31) + perm32(R & 31)) : R;
;         voffA[i] = (unsigned)(R * lda + C) * 2u; voffB[i] = (unsigned)(Rb * K + C) * 2u; }
;     const size_t kstep = (size_t)(BK * 2);
;     const size_t hstepA = (size_t)HALF * lda * 2, hstepB = (size_t)HALF * K * 2;
;     const size_t tstepA = 2 * hstepA, tstepB = 2 * hstepB;
;     const unsigned ldsw = (unsigned)wid * 1024u;
;     const int aoff = lds_byte(wr * 64 + fr, fq * 8), boff = lds_byte(wc * 32 + fr, fq * 8);
;     ...
;     Unit cur, nxt; int ui = 0;
;     if (!S.next(0, cur)) return;
;     f32x4 acc[2][2][4][2];
; #pragma unroll
;     for (int a = 0; a < 2; ++a)
; #pragma unroll
;         for (int b = 0; b < 2; ++b)
; #pragma unroll
;             for (int m = 0; m < 4; ++m)
; #pragma unroll
;                 for (int n = 0; n < 2; ++n) acc[a][b][m][n] = (f32x4){0.f, 0.f, 0.f, 0.f};
;     bf16x8 At[4][2], B0[2][2], B1[2][2];
;     const char* cA = (const char*)g.A + (size_t)cur.pm * tstepA + (size_t)cur.kt0 * kstep; const char* cB = (const char*)g.Bt + (size_t)cur.pn * tstepB + (size_t)cur.kt0 * kstep;
;     PG8_STAGE(PG8_SB(0, 0), cB, voffB); PG8_STAGE(PG8_SA(0, 0), cA, voffA); PG8_STAGE(PG8_SB(0, 1), cB + hstepB, voffB); PG8_STAGE(PG8_SA(0, 1), cA + hstepA, voffA);
;     if (wr == 1) PG8_BAR;
;     PG8_WAIT_V(4); PG8_BAR;
;     PG8_STAGE(PG8_SB(1, 0), cB + kstep, voffB); PG8_STAGE(PG8_SA(1, 0), cA + kstep, voffA); PG8_STAGE(PG8_SB(1, 1), cB + hstepB + kstep, voffB);
;     PG8_WAIT_V(6); PG8_BAR;
.LBB0_673:
	s_lshl_b32 s6, s6, 5
	s_mov_b64 s[28:29], 0x80
	s_and_b32 s36, s6, 0x60
	s_add_i32 m0, s35, 0x18000
	v_lshl_add_u64 v[6:7], v[6:7], 0, s[28:29]
	s_lshl_b32 s70, s1, 6
	s_lshl_b32 s1, s1, 13
	s_lshl_b32 s37, s36, 7
	s_waitcnt vmcnt(0)
	s_barrier
	global_load_lds_dwordx4 v[6:7], off
	v_lshl_add_u64 v[4:5], v[4:5], 0, s[28:29]
	s_add_i32 m0, s35, 0x1a000
	s_add_i32 s71, s35, 0x8000
	s_add_i32 s72, s35, 0xa000
	global_load_lds_dwordx4 v[4:5], off
	v_lshl_add_u64 v[2:3], v[2:3], 0, s[28:29]
	s_mov_b32 m0, s71
	s_add_u32 s6, s62, 0x40080
	global_load_lds_dwordx4 v[2:3], off
	v_lshl_add_u64 v[0:1], v[0:1], 0, s[28:29]
	s_mov_b32 m0, s72
	s_addc_u32 s7, s63, 0
	global_load_lds_dwordx4 v[0:1], off
	s_add_i32 m0, s35, 0x1c000
	v_lshl_add_u64 v[0:1], s[6:7], 0, v[138:139]
	global_load_lds_dwordx4 v[0:1], off
	v_lshl_add_u64 v[0:1], s[6:7], 0, v[142:143]
	s_add_i32 m0, s35, 0x1e000
	s_sext_i32_i8 s59, s0
	global_load_lds_dwordx4 v[0:1], off
	v_and_b32_e32 v135, 15, v129
	v_lshlrev_b32_e32 v0, 1, v11
	v_lshlrev_b32_e32 v2, 2, v129
	v_lshlrev_b32_e32 v3, 6, v129
	s_movk_i32 s0, 0x3c0
	v_lshl_or_b32 v1, v135, 6, v0
	v_and_b32_e32 v2, 32, v2
	v_and_or_b32 v0, v3, s0, v0
	v_bitop3_b32 v156, s37, v0, v2 bitop3:0xf6
	v_lshlrev_b32_e32 v0, 8, v129
	v_bitop3_b32 v1, v1, s1, v2 bitop3:0xde
	v_and_b32_e32 v0, 0x38000, v0
	v_lshlrev_b32_e32 v2, 11, v10
	v_or3_b32 v0, v8, v0, v2
	v_add_u32_e32 v144, v0, v9
	v_lshlrev_b32_e32 v0, 4, v12
	s_waitcnt vmcnt(6)
	v_and_b32_e32 v0, 0x78000, v0
	v_or3_b32 v0, v8, v0, v2
	s_add_i32 s75, 0, 0x10000
	s_add_i32 s76, 0, 0x14000
	v_cmp_lt_u32_e64 s[0:1], 13, v135
	v_add_u32_e32 v157, -14, v135
	s_ashr_i32 s73, s14, 31
	s_mov_b32 s74, s14
	v_or_b32_e32 v158, s36, v11
	v_mov_b32_e32 v145, v139
	v_add_u32_e32 v146, v0, v9
	v_mov_b32_e32 v147, v139
	v_mov_b64_e32 v[148:149], 0x5ac
	v_mov_b64_e32 v[150:151], 0x5ab
	v_add_u32_e32 v159, s75, v156
	v_add_u32_e32 v160, 0, v1
	v_add_u32_e32 v161, s76, v156
	s_movk_i32 s77, 0x2c00
	s_barrier
	s_mov_b32 s99, 0
	s_branch .LBB0_675

; #define PG8_STAGE(bufoff, gbase, voff) do { _Pragma("unroll") for (int _i = 0; _i < 2; ++_i) \
;         __builtin_amdgcn_global_load_lds((const unsigned*)((const char*)(gbase) + (voff)[_i]), (LAS unsigned*)(lds + (bufoff) + ldsw + _i * 8192), 16, 0, 0); } while (0)
; #define PG8_LDA(dst, b, h) do { _Pragma("unroll") for (int m = 0; m < 4; ++m) _Pragma("unroll") for (int k = 0; k < 2; ++k) dst[m][k] = *(const LAS bf16x8*)(lds + PG8_SA(b, h) + aoff + m * 2048 + k * 1024); } while (0)
; #define PG8_LDB(dst, b, h) do { _Pragma("unroll") for (int n = 0; n < 2; ++n) _Pragma("unroll") for (int k = 0; k < 2; ++k) dst[n][k] = *(const LAS bf16x8*)(lds + PG8_SB(b, h) + boff + n * 2048 + k * 1024); } while (0)
; #define PG8_MMA(ai, bj, At, Bt) do { __builtin_amdgcn_s_setprio(1); _Pragma("unroll") for (int m = 0; m < 4; ++m) _Pragma("unroll") for (int n = 0; n < 2; ++n) _Pragma("unroll") for (int k = 0; k < 2; ++k) \
;         acc[ai][bj][m][n] = __builtin_amdgcn_mfma_f32_16x16x32_bf16(Bt[n][k], At[m][k], acc[ai][bj][m][n], 0, 0, 0); __builtin_amdgcn_s_setprio(0); } while (0)
; #define PG8_WAIT_L(n) asm volatile("s_waitcnt lgkmcnt(" #n ")" ::: "memory")
; #define PG8_BAR __builtin_amdgcn_s_barrier()
; #define PG8_SCHED __builtin_amdgcn_sched_barrier(0)
; template <class Epi>
; __device__ __forceinline__ void gemm_phase(LAS unsigned char* lds, const Gemm g, const StaticOrder& S, const Epi& E) {
;     ...
;         const bool has_next = S.next(ui + 1, nxt);
;         const char* nA = has_next ? (const char*)g.A + (size_t)nxt.pm * tstepA + (size_t)nxt.kt0 * kstep : cA; const char* nB = has_next ? (const char*)g.Bt + (size_t)nxt.pn * tstepB + (size_t)nxt.kt0 * kstep : cB;
;         const int nt = cur.nkt;
;         for (int t = 0; t < nt; t += 2) {
;             const bool last = (t == nt - 2);
;             const char* a1 = cA + (size_t)(t + 1) * kstep;
;             const char* a2 = last ? nA : cA + (size_t)(t + 2) * kstep; const char* b2 = last ? nB : cB + (size_t)(t + 2) * kstep;
;             const char* a3 = a2 + kstep; const char* b3 = b2 + kstep;
;             PG8_LDB(B0, 0, 0); PG8_SCHED; PG8_LDA(At, 0, 0); PG8_STAGE(PG8_SA(1, 1), a1 + hstepA, voffA);
;             PG8_WAIT_L(8); PG8_BAR; PG8_WAIT_L(0); PG8_MMA(0, 0, At, B0); PG8_BAR; PG8_SCHED;
.LBB0_681:
	s_ashr_i32 s39, s38, 31
	v_cmp_lt_i64_e32 vcc, s[40:41], v[148:149]
	s_lshl_b64 s[40:41], s[38:39], 19
	s_add_u32 s37, s52, s40
	s_addc_u32 s39, s53, s41
	s_and_b64 s[40:41], vcc, exec
	s_cselect_b32 s41, s39, s61
	s_cselect_b32 s40, s37, s60
	s_ashr_i32 s37, s36, 31
	s_lshl_b64 s[56:57], s[36:37], 19
	s_add_u32 s37, s54, s56
	s_addc_u32 s39, s55, s57
	s_and_b64 s[56:57], vcc, exec
	s_cselect_b32 s57, s39, s63
	s_cselect_b32 s56, s37, s62
	s_add_u32 s60, s60, 0x40080
	s_addc_u32 s61, s61, 0
	s_add_u32 s37, s62, 0x100
	s_addc_u32 s39, s63, 0
	s_mov_b32 s78, -2
	s_add_u32 s62, s60, 0xfffc0080
	s_addc_u32 s63, s61, -1
	s_cmp_eq_u32 s78, 12
	s_cselect_b32 s65, s41, s63
	s_cselect_b32 s64, s40, s62
	s_cselect_b32 s63, s57, s39
	s_cselect_b32 s62, s56, s37
	ds_read_b128 v[152:155], v159
	ds_read_b128 v[162:165], v159 offset:1024
	ds_read_b128 v[166:169], v159 offset:2048
	ds_read_b128 v[170:173], v159 offset:3072
	ds_read_b128 v[174:177], v160
	ds_read_b128 v[178:181], v160 offset:1024
	ds_read_b128 v[182:185], v160 offset:2048
	ds_read_b128 v[186:189], v160 offset:3072
	ds_read_b128 v[190:193], v160 offset:4096
	ds_read_b128 v[194:197], v160 offset:5120
	ds_read_b128 v[198:201], v160 offset:6144
	ds_read_b128 v[202:205], v160 offset:7168
	ds_read_b128 v[206:209], v161
	ds_read_b128 v[210:213], v161 offset:1024
	ds_read_b128 v[214:217], v161 offset:2048
	ds_read_b128 v[218:221], v161 offset:3072
	s_add_i32 m0, s35, 0xc000
	v_lshl_add_u64 v[242:243], s[60:61], 0, v[144:145]
	global_load_lds_dwordx4 v[242:243], off
	s_add_i32 m0, s35, 0xe000
	v_lshl_add_u64 v[242:243], s[60:61], 0, v[146:147]
	global_load_lds_dwordx4 v[242:243], off
	s_cmp_eq_u32 s99, 0
	s_cbranch_scc1 .Lrw2_0s
	s_waitcnt vmcnt(24) lgkmcnt(0)
	s_branch .Lrw2_0d

; #define PG8_STAGE(bufoff, gbase, voff) do { _Pragma("unroll") for (int _i = 0; _i < 2; ++_i) \
;         __builtin_amdgcn_global_load_lds((const unsigned*)((const char*)(gbase) + (voff)[_i]), (LAS unsigned*)(lds + (bufoff) + ldsw + _i * 8192), 16, 0, 0); } while (0)
; #define PG8_LDA(dst, b, h) do { _Pragma("unroll") for (int m = 0; m < 4; ++m) _Pragma("unroll") for (int k = 0; k < 2; ++k) dst[m][k] = *(const LAS bf16x8*)(lds + PG8_SA(b, h) + aoff + m * 2048 + k * 1024); } while (0)
; #define PG8_LDB(dst, b, h) do { _Pragma("unroll") for (int n = 0; n < 2; ++n) _Pragma("unroll") for (int k = 0; k < 2; ++k) dst[n][k] = *(const LAS bf16x8*)(lds + PG8_SB(b, h) + boff + n * 2048 + k * 1024); } while (0)
; #define PG8_MMA(ai, bj, At, Bt) do { __builtin_amdgcn_s_setprio(1); _Pragma("unroll") for (int m = 0; m < 4; ++m) _Pragma("unroll") for (int n = 0; n < 2; ++n) _Pragma("unroll") for (int k = 0; k < 2; ++k) \
;         acc[ai][bj][m][n] = __builtin_amdgcn_mfma_f32_16x16x32_bf16(Bt[n][k], At[m][k], acc[ai][bj][m][n], 0, 0, 0); __builtin_amdgcn_s_setprio(0); } while (0)
; #define PG8_WAIT_L(n) asm volatile("s_waitcnt lgkmcnt(" #n ")" ::: "memory")
; #define PG8_BAR __builtin_amdgcn_s_barrier()
; #define PG8_SCHED __builtin_amdgcn_sched_barrier(0)
; template <class Epi>
; __device__ __forceinline__ void gemm_phase(LAS unsigned char* lds, const Gemm g, const StaticOrder& S, const Epi& E) {
;     ...
;             PG8_LDB(B0, 0, 0); PG8_SCHED; PG8_LDA(At, 0, 0); PG8_STAGE(PG8_SA(1, 1), a1 + hstepA, voffA);
;             PG8_WAIT_L(8); PG8_BAR; PG8_WAIT_L(0); PG8_MMA(0, 0, At, B0); PG8_BAR; PG8_SCHED;
;             PG8_LDB(B1, 0, 1); PG8_STAGE(PG8_SB(0, 0), b2, voffB);
;             PG8_BAR; PG8_WAIT_L(0); PG8_MMA(0, 1, At, B1); PG8_BAR;
;             PG8_LDA(At, 0, 1); PG8_STAGE(PG8_SA(0, 0), a2, voffA);
;             PG8_BAR; PG8_WAIT_L(0); PG8_MMA(1, 0, At, B0); PG8_BAR; PG8_SCHED;
.Lrw2_0d:
	s_barrier
	v_mfma_f32_16x16x32_bf16 v[124:127], v[152:155], v[174:177], 0
	v_mfma_f32_16x16x32_bf16 v[120:123], v[166:169], v[174:177], 0
	v_mfma_f32_16x16x32_bf16 v[116:119], v[152:155], v[182:185], 0
	v_mfma_f32_16x16x32_bf16 v[108:111], v[166:169], v[182:185], 0
	v_mfma_f32_16x16x32_bf16 v[100:103], v[152:155], v[190:193], 0
	v_mfma_f32_16x16x32_bf16 v[92:95], v[166:169], v[190:193], 0
	v_mfma_f32_16x16x32_bf16 v[84:87], v[152:155], v[198:201], 0
	v_mfma_f32_16x16x32_bf16 v[76:79], v[166:169], v[198:201], 0
	v_mfma_f32_16x16x32_bf16 v[124:127], v[162:165], v[178:181], v[124:127]
	v_mfma_f32_16x16x32_bf16 v[120:123], v[170:173], v[178:181], v[120:123]
	v_mfma_f32_16x16x32_bf16 v[116:119], v[162:165], v[186:189], v[116:119]
	v_mfma_f32_16x16x32_bf16 v[108:111], v[170:173], v[186:189], v[108:111]
	v_mfma_f32_16x16x32_bf16 v[100:103], v[162:165], v[194:197], v[100:103]
	v_mfma_f32_16x16x32_bf16 v[92:95], v[170:173], v[194:197], v[92:95]
	v_mfma_f32_16x16x32_bf16 v[84:87], v[162:165], v[202:205], v[84:87]
	v_mfma_f32_16x16x32_bf16 v[76:79], v[170:173], v[202:205], v[76:79]
	v_mfma_f32_16x16x32_bf16 v[112:115], v[206:209], v[174:177], 0
	v_mfma_f32_16x16x32_bf16 v[104:107], v[214:217], v[174:177], 0
	v_mfma_f32_16x16x32_bf16 v[96:99], v[206:209], v[182:185], 0
	v_mfma_f32_16x16x32_bf16 v[88:91], v[214:217], v[182:185], 0
	v_mfma_f32_16x16x32_bf16 v[80:83], v[206:209], v[190:193], 0
	v_mfma_f32_16x16x32_bf16 v[72:75], v[214:217], v[190:193], 0
	v_mfma_f32_16x16x32_bf16 v[68:71], v[206:209], v[198:201], 0
	v_mfma_f32_16x16x32_bf16 v[64:67], v[214:217], v[198:201], 0
	v_mfma_f32_16x16x32_bf16 v[112:115], v[210:213], v[178:181], v[112:115]
	v_mfma_f32_16x16x32_bf16 v[104:107], v[218:221], v[178:181], v[104:107]
	v_mfma_f32_16x16x32_bf16 v[96:99], v[210:213], v[186:189], v[96:99]
	v_mfma_f32_16x16x32_bf16 v[88:91], v[218:221], v[186:189], v[88:91]
	v_mfma_f32_16x16x32_bf16 v[80:83], v[210:213], v[194:197], v[80:83]
	v_mfma_f32_16x16x32_bf16 v[72:75], v[218:221], v[194:197], v[72:75]
	v_mfma_f32_16x16x32_bf16 v[68:71], v[210:213], v[202:205], v[68:71]
	v_mfma_f32_16x16x32_bf16 v[64:67], v[218:221], v[202:205], v[64:67]
	s_barrier
	ds_read_b128 v[174:177], v160 offset:16384
	ds_read_b128 v[178:181], v160 offset:17408
	ds_read_b128 v[182:185], v160 offset:18432
	ds_read_b128 v[186:189], v160 offset:19456
	ds_read_b128 v[190:193], v160 offset:20480
	ds_read_b128 v[194:197], v160 offset:21504
	ds_read_b128 v[198:201], v160 offset:22528
	ds_read_b128 v[202:205], v160 offset:23552
	s_add_i32 s79, s75, s33
	s_mov_b32 m0, s79
	v_lshl_add_u64 v[222:223], s[62:63], 0, v[138:139]
	global_load_lds_dwordx4 v[222:223], off
	s_add_i32 m0, s79, 0x2000
	v_lshl_add_u64 v[224:225], s[62:63], 0, v[142:143]
	global_load_lds_dwordx4 v[224:225], off
	s_mov_b32 m0, s35
	v_lshl_add_u64 v[226:227], s[64:65], 0, v[136:137]
	global_load_lds_dwordx4 v[226:227], off
	s_mov_b32 m0, s66
	v_lshl_add_u64 v[228:229], s[64:65], 0, v[140:141]
	global_load_lds_dwordx4 v[228:229], off
	s_add_u32 s80, s62, 0x40000
	s_addc_u32 s81, s63, 0
	s_add_i32 s79, s76, s33
	s_mov_b32 m0, s79
	v_lshl_add_u64 v[240:241], s[80:81], 0, v[138:139]
	global_load_lds_dwordx4 v[240:241], off
	s_add_i32 m0, s79, 0x2000
	v_lshl_add_u64 v[240:241], s[80:81], 0, v[142:143]
	global_load_lds_dwordx4 v[240:241], off
	s_cmp_eq_u32 s99, 0
	s_cbranch_scc1 .Lrw2_1s
	s_waitcnt vmcnt(24) lgkmcnt(0)
	s_branch .Lrw2_1d

; #define PG8_STAGE(bufoff, gbase, voff) do { _Pragma("unroll") for (int _i = 0; _i < 2; ++_i) \
;         __builtin_amdgcn_global_load_lds((const unsigned*)((const char*)(gbase) + (voff)[_i]), (LAS unsigned*)(lds + (bufoff) + ldsw + _i * 8192), 16, 0, 0); } while (0)
; #define PG8_LDA(dst, b, h) do { _Pragma("unroll") for (int m = 0; m < 4; ++m) _Pragma("unroll") for (int k = 0; k < 2; ++k) dst[m][k] = *(const LAS bf16x8*)(lds + PG8_SA(b, h) + aoff + m * 2048 + k * 1024); } while (0)
; #define PG8_LDB(dst, b, h) do { _Pragma("unroll") for (int n = 0; n < 2; ++n) _Pragma("unroll") for (int k = 0; k < 2; ++k) dst[n][k] = *(const LAS bf16x8*)(lds + PG8_SB(b, h) + boff + n * 2048 + k * 1024); } while (0)
; #define PG8_MMA(ai, bj, At, Bt) do { __builtin_amdgcn_s_setprio(1); _Pragma("unroll") for (int m = 0; m < 4; ++m) _Pragma("unroll") for (int n = 0; n < 2; ++n) _Pragma("unroll") for (int k = 0; k < 2; ++k) \
;         acc[ai][bj][m][n] = __builtin_amdgcn_mfma_f32_16x16x32_bf16(Bt[n][k], At[m][k], acc[ai][bj][m][n], 0, 0, 0); __builtin_amdgcn_s_setprio(0); } while (0)
; #define PG8_WAIT_V(n) asm volatile("s_waitcnt vmcnt(" #n ")" ::: "memory")
; #define PG8_WAIT_L(n) asm volatile("s_waitcnt lgkmcnt(" #n ")" ::: "memory")
; #define PG8_BAR __builtin_amdgcn_s_barrier()
; #define PG8_SCHED __builtin_amdgcn_sched_barrier(0)
; template <class Epi>
; __device__ __forceinline__ void gemm_phase(LAS unsigned char* lds, const Gemm g, const StaticOrder& S, const Epi& E) {
;     ...
;             PG8_BAR; PG8_WAIT_L(0); PG8_MMA(0, 1, At, B1); PG8_BAR;
;             PG8_LDA(At, 0, 1); PG8_STAGE(PG8_SA(0, 0), a2, voffA);
;             PG8_BAR; PG8_WAIT_L(0); PG8_MMA(1, 0, At, B0); PG8_BAR; PG8_SCHED;
;             PG8_STAGE(PG8_SB(0, 1), b2 + hstepB, voffB);
;             PG8_WAIT_V(6); PG8_BAR; PG8_MMA(1, 1, At, B1); PG8_BAR;
;             PG8_LDB(B0, 1, 0); PG8_SCHED; PG8_LDA(At, 1, 0); PG8_STAGE(PG8_SA(0, 1), a2 + hstepA, voffA);
;             PG8_WAIT_L(8); PG8_BAR; PG8_WAIT_L(0); PG8_MMA(0, 0, At, B0); PG8_BAR; PG8_SCHED;
.Lrw2_1d:
	s_mov_b32 s99, 1
	s_barrier
	v_mfma_f32_16x16x32_bf16 v[60:63], v[152:155], v[174:177], 0
	v_mfma_f32_16x16x32_bf16 v[56:59], v[166:169], v[174:177], 0
	v_mfma_f32_16x16x32_bf16 v[52:55], v[152:155], v[182:185], 0
	v_mfma_f32_16x16x32_bf16 v[44:47], v[166:169], v[182:185], 0
	v_mfma_f32_16x16x32_bf16 v[36:39], v[152:155], v[190:193], 0
	v_mfma_f32_16x16x32_bf16 v[28:31], v[166:169], v[190:193], 0
	v_mfma_f32_16x16x32_bf16 v[20:23], v[152:155], v[198:201], 0
	v_mfma_f32_16x16x32_bf16 v[12:15], v[166:169], v[198:201], 0
	v_mfma_f32_16x16x32_bf16 v[60:63], v[162:165], v[178:181], v[60:63]
	v_mfma_f32_16x16x32_bf16 v[56:59], v[170:173], v[178:181], v[56:59]
	v_mfma_f32_16x16x32_bf16 v[52:55], v[162:165], v[186:189], v[52:55]
	v_mfma_f32_16x16x32_bf16 v[44:47], v[170:173], v[186:189], v[44:47]
	v_mfma_f32_16x16x32_bf16 v[36:39], v[162:165], v[194:197], v[36:39]
	v_mfma_f32_16x16x32_bf16 v[28:31], v[170:173], v[194:197], v[28:31]
	v_mfma_f32_16x16x32_bf16 v[20:23], v[162:165], v[202:205], v[20:23]
	v_mfma_f32_16x16x32_bf16 v[12:15], v[170:173], v[202:205], v[12:15]
	v_mfma_f32_16x16x32_bf16 v[48:51], v[206:209], v[174:177], 0
	v_mfma_f32_16x16x32_bf16 v[40:43], v[214:217], v[174:177], 0
	v_mfma_f32_16x16x32_bf16 v[32:35], v[206:209], v[182:185], 0
	v_mfma_f32_16x16x32_bf16 v[24:27], v[214:217], v[182:185], 0
	v_mfma_f32_16x16x32_bf16 v[16:19], v[206:209], v[190:193], 0
	v_mfma_f32_16x16x32_bf16 v[8:11], v[214:217], v[190:193], 0
	v_mfma_f32_16x16x32_bf16 v[4:7], v[206:209], v[198:201], 0
	v_mfma_f32_16x16x32_bf16 v[0:3], v[214:217], v[198:201], 0
	v_mfma_f32_16x16x32_bf16 v[48:51], v[210:213], v[178:181], v[48:51]
	v_mfma_f32_16x16x32_bf16 v[40:43], v[218:221], v[178:181], v[40:43]
	v_mfma_f32_16x16x32_bf16 v[32:35], v[210:213], v[186:189], v[32:35]
	v_mfma_f32_16x16x32_bf16 v[24:27], v[218:221], v[186:189], v[24:27]
	v_mfma_f32_16x16x32_bf16 v[16:19], v[210:213], v[194:197], v[16:19]
	v_mfma_f32_16x16x32_bf16 v[8:11], v[218:221], v[194:197], v[8:11]
	v_mfma_f32_16x16x32_bf16 v[4:7], v[210:213], v[202:205], v[4:7]
	v_mfma_f32_16x16x32_bf16 v[0:3], v[218:221], v[202:205], v[0:3]
	s_barrier
	s_add_i32 s79, 0, 0x18000
	v_add_u32_e32 v170, s79, v156
	ds_read_b128 v[152:155], v170
	ds_read_b128 v[162:165], v170 offset:1024
	ds_read_b128 v[166:169], v170 offset:2048
	ds_read_b128 v[170:173], v170 offset:3072
	ds_read_b128 v[174:177], v160 offset:32768
	ds_read_b128 v[178:181], v160 offset:33792
	ds_read_b128 v[182:185], v160 offset:34816
	ds_read_b128 v[186:189], v160 offset:35840
	ds_read_b128 v[190:193], v160 offset:36864
	ds_read_b128 v[194:197], v160 offset:37888
	ds_read_b128 v[198:201], v160 offset:38912
	ds_read_b128 v[202:205], v160 offset:39936
	s_add_i32 s98, 0, 0x1c000
	v_add_u32_e32 v218, s98, v156
	ds_read_b128 v[206:209], v218
	ds_read_b128 v[210:213], v218 offset:1024
	ds_read_b128 v[214:217], v218 offset:2048
	ds_read_b128 v[218:221], v218 offset:3072
	s_add_u32 s64, s64, 0x40000
	s_addc_u32 s65, s65, 0
	s_mov_b32 m0, s67
	v_lshl_add_u64 v[244:245], s[64:65], 0, v[136:137]
	global_load_lds_dwordx4 v[244:245], off
	s_mov_b32 m0, s68
	v_lshl_add_u64 v[244:245], s[64:65], 0, v[140:141]
	global_load_lds_dwordx4 v[244:245], off
	s_waitcnt vmcnt(8) lgkmcnt(0)
	s_barrier
	v_mfma_f32_16x16x32_bf16 v[124:127], v[152:155], v[174:177], v[124:127]
	v_mfma_f32_16x16x32_bf16 v[120:123], v[166:169], v[174:177], v[120:123]
	v_mfma_f32_16x16x32_bf16 v[116:119], v[152:155], v[182:185], v[116:119]
	v_mfma_f32_16x16x32_bf16 v[108:111], v[166:169], v[182:185], v[108:111]
	v_mfma_f32_16x16x32_bf16 v[100:103], v[152:155], v[190:193], v[100:103]
	v_mfma_f32_16x16x32_bf16 v[92:95], v[166:169], v[190:193], v[92:95]
	v_mfma_f32_16x16x32_bf16 v[84:87], v[152:155], v[198:201], v[84:87]
	v_mfma_f32_16x16x32_bf16 v[76:79], v[166:169], v[198:201], v[76:79]
	v_mfma_f32_16x16x32_bf16 v[124:127], v[162:165], v[178:181], v[124:127]
	v_mfma_f32_16x16x32_bf16 v[120:123], v[170:173], v[178:181], v[120:123]
	v_mfma_f32_16x16x32_bf16 v[116:119], v[162:165], v[186:189], v[116:119]
	v_mfma_f32_16x16x32_bf16 v[108:111], v[170:173], v[186:189], v[108:111]
	v_mfma_f32_16x16x32_bf16 v[100:103], v[162:165], v[194:197], v[100:103]
	v_mfma_f32_16x16x32_bf16 v[92:95], v[170:173], v[194:197], v[92:95]
	v_mfma_f32_16x16x32_bf16 v[84:87], v[162:165], v[202:205], v[84:87]
	v_mfma_f32_16x16x32_bf16 v[76:79], v[170:173], v[202:205], v[76:79]
	v_mfma_f32_16x16x32_bf16 v[112:115], v[206:209], v[174:177], v[112:115]
	v_mfma_f32_16x16x32_bf16 v[104:107], v[214:217], v[174:177], v[104:107]
	v_mfma_f32_16x16x32_bf16 v[96:99], v[206:209], v[182:185], v[96:99]
	v_mfma_f32_16x16x32_bf16 v[88:91], v[214:217], v[182:185], v[88:91]
	v_mfma_f32_16x16x32_bf16 v[80:83], v[206:209], v[190:193], v[80:83]
	v_mfma_f32_16x16x32_bf16 v[72:75], v[214:217], v[190:193], v[72:75]
	v_mfma_f32_16x16x32_bf16 v[68:71], v[206:209], v[198:201], v[68:71]
	v_mfma_f32_16x16x32_bf16 v[64:67], v[214:217], v[198:201], v[64:67]
	v_mfma_f32_16x16x32_bf16 v[112:115], v[210:213], v[178:181], v[112:115]
	v_mfma_f32_16x16x32_bf16 v[104:107], v[218:221], v[178:181], v[104:107]
	v_mfma_f32_16x16x32_bf16 v[96:99], v[210:213], v[186:189], v[96:99]
	v_mfma_f32_16x16x32_bf16 v[88:91], v[218:221], v[186:189], v[88:91]
	v_mfma_f32_16x16x32_bf16 v[80:83], v[210:213], v[194:197], v[80:83]
	v_mfma_f32_16x16x32_bf16 v[72:75], v[218:221], v[194:197], v[72:75]
	v_mfma_f32_16x16x32_bf16 v[68:71], v[210:213], v[202:205], v[68:71]
	v_mfma_f32_16x16x32_bf16 v[64:67], v[218:221], v[202:205], v[64:67]
	s_barrier
; #define PG8_STAGE(bufoff, gbase, voff) do { _Pragma("unroll") for (int _i = 0; _i < 2; ++_i) \
;         __builtin_amdgcn_global_load_lds((const unsigned*)((const char*)(gbase) + (voff)[_i]), (LAS unsigned*)(lds + (bufoff) + ldsw + _i * 8192), 16, 0, 0); } while (0)
; #define PG8_LDA(dst, b, h) do { _Pragma("unroll") for (int m = 0; m < 4; ++m) _Pragma("unroll") for (int k = 0; k < 2; ++k) dst[m][k] = *(const LAS bf16x8*)(lds + PG8_SA(b, h) + aoff + m * 2048 + k * 1024); } while (0)
; #define PG8_LDB(dst, b, h) do { _Pragma("unroll") for (int n = 0; n < 2; ++n) _Pragma("unroll") for (int k = 0; k < 2; ++k) dst[n][k] = *(const LAS bf16x8*)(lds + PG8_SB(b, h) + boff + n * 2048 + k * 1024); } while (0)
; #define PG8_MMA(ai, bj, At, Bt) do { __builtin_amdgcn_s_setprio(1); _Pragma("unroll") for (int m = 0; m < 4; ++m) _Pragma("unroll") for (int n = 0; n < 2; ++n) _Pragma("unroll") for (int k = 0; k < 2; ++k) \
;         acc[ai][bj][m][n] = __builtin_amdgcn_mfma_f32_16x16x32_bf16(Bt[n][k], At[m][k], acc[ai][bj][m][n], 0, 0, 0); __builtin_amdgcn_s_setprio(0); } while (0)
; #define PG8_WAIT_V(n) asm volatile("s_waitcnt vmcnt(" #n ")" ::: "memory")
; #define PG8_WAIT_L(n) asm volatile("s_waitcnt lgkmcnt(" #n ")" ::: "memory")
; #define PG8_BAR __builtin_amdgcn_s_barrier()
; #define PG8_SCHED __builtin_amdgcn_sched_barrier(0)
; template <class Epi>
; __device__ __forceinline__ void gemm_phase(LAS unsigned char* lds, const Gemm g, const StaticOrder& S, const Epi& E) {
;     ...
;             PG8_LDB(B1, 1, 1); PG8_STAGE(PG8_SB(1, 0), b3, voffB);
;             PG8_BAR; PG8_WAIT_L(0); PG8_MMA(0, 1, At, B1); PG8_BAR;
;             PG8_LDA(At, 1, 1); PG8_STAGE(PG8_SA(1, 0), a3, voffA);
;             PG8_BAR; PG8_WAIT_L(0); PG8_MMA(1, 0, At, B0); PG8_BAR; PG8_SCHED;
;             PG8_STAGE(PG8_SB(1, 1), b3 + hstepB, voffB);
;             PG8_WAIT_V(6); PG8_BAR; PG8_MMA(1, 1, At, B1); PG8_BAR;
	ds_read_b128 v[174:177], v160 offset:49152
	ds_read_b128 v[178:181], v160 offset:50176
	ds_read_b128 v[182:185], v160 offset:51200
	ds_read_b128 v[186:189], v160 offset:52224
	ds_read_b128 v[190:193], v160 offset:53248
	ds_read_b128 v[194:197], v160 offset:54272
	ds_read_b128 v[198:201], v160 offset:55296
	ds_read_b128 v[202:205], v160 offset:56320
	s_add_i32 s65, s79, s33
	s_mov_b32 m0, s65
	v_lshl_add_u64 v[222:223], v[222:223], 0, s[28:29]
	global_load_lds_dwordx4 v[222:223], off
	s_add_i32 m0, s65, 0x2000
	v_lshl_add_u64 v[222:223], v[224:225], 0, s[28:29]
	global_load_lds_dwordx4 v[222:223], off
	s_mov_b32 m0, s71
	v_lshl_add_u64 v[222:223], v[226:227], 0, s[28:29]
	global_load_lds_dwordx4 v[222:223], off
	s_mov_b32 m0, s72
	v_lshl_add_u64 v[222:223], v[228:229], 0, s[28:29]
	global_load_lds_dwordx4 v[222:223], off
	s_add_u32 s62, s62, 0x40080
	s_addc_u32 s63, s63, 0
	s_add_i32 s64, s98, s33
	s_mov_b32 m0, s64
	v_lshl_add_u64 v[240:241], s[62:63], 0, v[138:139]
	global_load_lds_dwordx4 v[240:241], off
	s_add_i32 m0, s64, 0x2000
	v_lshl_add_u64 v[240:241], s[62:63], 0, v[142:143]
	global_load_lds_dwordx4 v[240:241], off
	s_waitcnt vmcnt(8) lgkmcnt(0)
	s_barrier
	v_mfma_f32_16x16x32_bf16 v[60:63], v[152:155], v[174:177], v[60:63]
	v_mfma_f32_16x16x32_bf16 v[56:59], v[166:169], v[174:177], v[56:59]
	v_mfma_f32_16x16x32_bf16 v[52:55], v[152:155], v[182:185], v[52:55]
	v_mfma_f32_16x16x32_bf16 v[44:47], v[166:169], v[182:185], v[44:47]
	v_mfma_f32_16x16x32_bf16 v[36:39], v[152:155], v[190:193], v[36:39]
	v_mfma_f32_16x16x32_bf16 v[28:31], v[166:169], v[190:193], v[28:31]
	v_mfma_f32_16x16x32_bf16 v[20:23], v[152:155], v[198:201], v[20:23]
	v_mfma_f32_16x16x32_bf16 v[12:15], v[166:169], v[198:201], v[12:15]
	v_mfma_f32_16x16x32_bf16 v[60:63], v[162:165], v[178:181], v[60:63]
	v_mfma_f32_16x16x32_bf16 v[56:59], v[170:173], v[178:181], v[56:59]
	v_mfma_f32_16x16x32_bf16 v[52:55], v[162:165], v[186:189], v[52:55]
	v_mfma_f32_16x16x32_bf16 v[44:47], v[170:173], v[186:189], v[44:47]
	v_mfma_f32_16x16x32_bf16 v[36:39], v[162:165], v[194:197], v[36:39]
	v_mfma_f32_16x16x32_bf16 v[28:31], v[170:173], v[194:197], v[28:31]
	v_mfma_f32_16x16x32_bf16 v[20:23], v[162:165], v[202:205], v[20:23]
	v_mfma_f32_16x16x32_bf16 v[12:15], v[170:173], v[202:205], v[12:15]
	v_mfma_f32_16x16x32_bf16 v[48:51], v[206:209], v[174:177], v[48:51]
	v_mfma_f32_16x16x32_bf16 v[40:43], v[214:217], v[174:177], v[40:43]
	v_mfma_f32_16x16x32_bf16 v[32:35], v[206:209], v[182:185], v[32:35]
	v_mfma_f32_16x16x32_bf16 v[24:27], v[214:217], v[182:185], v[24:27]
	v_mfma_f32_16x16x32_bf16 v[16:19], v[206:209], v[190:193], v[16:19]
	v_mfma_f32_16x16x32_bf16 v[8:11], v[214:217], v[190:193], v[8:11]
	v_mfma_f32_16x16x32_bf16 v[4:7], v[206:209], v[198:201], v[4:7]
	v_mfma_f32_16x16x32_bf16 v[0:3], v[214:217], v[198:201], v[0:3]
	v_mfma_f32_16x16x32_bf16 v[48:51], v[210:213], v[178:181], v[48:51]
	v_mfma_f32_16x16x32_bf16 v[40:43], v[218:221], v[178:181], v[40:43]
	v_mfma_f32_16x16x32_bf16 v[32:35], v[210:213], v[186:189], v[32:35]
	v_mfma_f32_16x16x32_bf16 v[24:27], v[218:221], v[186:189], v[24:27]
	v_mfma_f32_16x16x32_bf16 v[16:19], v[210:213], v[194:197], v[16:19]
	v_mfma_f32_16x16x32_bf16 v[8:11], v[218:221], v[194:197], v[8:11]
	v_mfma_f32_16x16x32_bf16 v[4:7], v[210:213], v[202:205], v[4:7]
	v_mfma_f32_16x16x32_bf16 v[0:3], v[218:221], v[202:205], v[0:3]
	s_add_i32 s78, s78, 2
	s_add_u32 s60, s60, 0x100
	s_addc_u32 s61, s61, 0
	s_add_u32 s37, s37, 0x100
	s_addc_u32 s39, s39, 0
	s_cmp_gt_u32 s78, 13
	s_barrier

; #define PG8_STAGE(bufoff, gbase, voff) do { _Pragma("unroll") for (int _i = 0; _i < 2; ++_i) \
;         __builtin_amdgcn_global_load_lds((const unsigned*)((const char*)(gbase) + (voff)[_i]), (LAS unsigned*)(lds + (bufoff) + ldsw + _i * 8192), 16, 0, 0); } while (0)
; #define PG8_WAIT_V(n) asm volatile("s_waitcnt vmcnt(" #n ")" ::: "memory")
; #define PG8_BAR __builtin_amdgcn_s_barrier()
; template <class Epi>
; __device__ __forceinline__ void gemm_phase(LAS unsigned char* lds, const Gemm g, const StaticOrder& S, const Epi& E) {
;     ...
;     for (int i = 0; i < 2; ++i) { int R, C; stage_rc(tid * 16 + i * 8192, R, C); const int Rb = Epi::PERM ? ((R & ~31) + perm32(R & 31)) : R;
;         voffA[i] = (unsigned)(R * lda + C) * 2u; voffB[i] = (unsigned)(Rb * K + C) * 2u; }
;     const size_t kstep = (size_t)(BK * 2);
;     const size_t hstepA = (size_t)HALF * lda * 2, hstepB = (size_t)HALF * K * 2;
;     const size_t tstepA = 2 * hstepA, tstepB = 2 * hstepB;
;     const unsigned ldsw = (unsigned)wid * 1024u;
;     const int aoff = lds_byte(wr * 64 + fr, fq * 8), boff = lds_byte(wc * 32 + fr, fq * 8);
;     ...
;     Unit cur, nxt; int ui = 0;
;     if (!S.next(0, cur)) return;
;     f32x4 acc[2][2][4][2];
; #pragma unroll
;     for (int a = 0; a < 2; ++a)
; #pragma unroll
;         for (int b = 0; b < 2; ++b)
; #pragma unroll
;             for (int m = 0; m < 4; ++m)
; #pragma unroll
;                 for (int n = 0; n < 2; ++n) acc[a][b][m][n] = (f32x4){0.f, 0.f, 0.f, 0.f};
;     bf16x8 At[4][2], B0[2][2], B1[2][2];
;     const char* cA = (const char*)g.A + (size_t)cur.pm * tstepA + (size_t)cur.kt0 * kstep; const char* cB = (const char*)g.Bt + (size_t)cur.pn * tstepB + (size_t)cur.kt0 * kstep;
;     PG8_STAGE(PG8_SB(0, 0), cB, voffB); PG8_STAGE(PG8_SA(0, 0), cA, voffA); PG8_STAGE(PG8_SB(0, 1), cB + hstepB, voffB); PG8_STAGE(PG8_SA(0, 1), cA + hstepA, voffA);
;     if (wr == 1) PG8_BAR;
;     PG8_WAIT_V(4); PG8_BAR;
;     PG8_STAGE(PG8_SB(1, 0), cB + kstep, voffB); PG8_STAGE(PG8_SA(1, 0), cA + kstep, voffA); PG8_STAGE(PG8_SB(1, 1), cB + hstepB + kstep, voffB);
;     PG8_WAIT_V(6); PG8_BAR;
.LBB0_893:
	s_lshl_b32 s0, s22, 5
	s_mov_b64 s[22:23], 0x80
	s_add_i32 m0, s33, 0x18000
	v_lshl_add_u64 v[6:7], v[6:7], 0, s[22:23]
	s_lshl_b32 s24, s18, 13
	s_and_b32 s25, s0, 0x60
	s_waitcnt vmcnt(0)
	s_barrier
	global_load_lds_dwordx4 v[6:7], off
	v_lshl_add_u64 v[4:5], v[4:5], 0, s[22:23]
	s_add_i32 m0, s33, 0x1a000
	s_add_i32 s60, s33, 0x8000
	s_add_i32 s61, s33, 0xa000
	global_load_lds_dwordx4 v[4:5], off
	v_lshl_add_u64 v[0:1], v[0:1], 0, s[22:23]
	s_mov_b32 m0, s60
	s_add_u32 s0, s54, 0xb0080
	global_load_lds_dwordx4 v[0:1], off
	v_lshl_add_u64 v[0:1], v[2:3], 0, s[22:23]
	s_mov_b32 m0, s61
	s_addc_u32 s1, s55, 0
	global_load_lds_dwordx4 v[0:1], off
	s_add_i32 m0, s33, 0x1c000
	v_lshl_add_u64 v[0:1], s[0:1], 0, v[138:139]
	global_load_lds_dwordx4 v[0:1], off
	v_lshl_add_u64 v[0:1], s[0:1], 0, v[142:143]
	s_add_i32 m0, s33, 0x1e000
	v_lshl_or_b32 v168, s25, 7, v160
	global_load_lds_dwordx4 v[0:1], off
	v_lshlrev_b32_e32 v1, 2, v161
	v_lshl_or_b32 v0, v161, 6, v135
	v_and_b32_e32 v1, 32, v1
	v_bitop3_b32 v0, v0, s24, v1 bitop3:0xde
	s_waitcnt vmcnt(6)
	v_add_u16_e32 v1, v8, v9
	v_lshrrev_b16_e32 v1, 1, v1
	s_add_i32 s65, 0, 0x10000
	s_add_i32 s66, 0, 0x14000
	v_lshl_or_b32 v167, s18, 6, v161
	s_ashr_i32 s62, s14, 31
	s_mov_b32 s63, s14
	s_ashr_i32 s64, s2, 31
	v_or_b32_e32 v169, s25, v133
	v_add_lshl_u32 v144, v10, v1, 1
	v_mov_b32_e32 v145, v139
	v_add_lshl_u32 v146, v11, v1, 1
	v_mov_b32_e32 v147, v139
	v_mov_b64_e32 v[148:149], 0xff
	v_add_u32_e32 v170, s65, v168
	v_add_u32_e32 v171, 0, v0
	v_add_u32_e32 v172, s66, v168
	s_mov_b32 s67, 0x90000
	s_mov_b64 s[24:25], 0xa0000
	s_mov_b32 s68, 0xa0000
	s_mov_b64 s[26:27], 0x40000
	s_mov_b32 s69, 0x40000
	s_mov_b64 s[28:29], 0x48000
	s_mov_b32 s70, 0x48000
	s_mov_b64 s[36:37], 0x50000
	s_mov_b32 s71, 0x50000
	s_mov_b64 s[38:39], 0x58000
	s_mov_b32 s72, 0x58000
	s_mov_b32 s73, 0
	s_barrier
	s_mov_b32 s99, 0
	s_branch .LBB0_896

; #define PG8_STAGE(bufoff, gbase, voff) do { _Pragma("unroll") for (int _i = 0; _i < 2; ++_i) \
;         __builtin_amdgcn_global_load_lds((const unsigned*)((const char*)(gbase) + (voff)[_i]), (LAS unsigned*)(lds + (bufoff) + ldsw + _i * 8192), 16, 0, 0); } while (0)
; #define PG8_LDA(dst, b, h) do { _Pragma("unroll") for (int m = 0; m < 4; ++m) _Pragma("unroll") for (int k = 0; k < 2; ++k) dst[m][k] = *(const LAS bf16x8*)(lds + PG8_SA(b, h) + aoff + m * 2048 + k * 1024); } while (0)
; #define PG8_LDB(dst, b, h) do { _Pragma("unroll") for (int n = 0; n < 2; ++n) _Pragma("unroll") for (int k = 0; k < 2; ++k) dst[n][k] = *(const LAS bf16x8*)(lds + PG8_SB(b, h) + boff + n * 2048 + k * 1024); } while (0)
; #define PG8_MMA(ai, bj, At, Bt) do { __builtin_amdgcn_s_setprio(1); _Pragma("unroll") for (int m = 0; m < 4; ++m) _Pragma("unroll") for (int n = 0; n < 2; ++n) _Pragma("unroll") for (int k = 0; k < 2; ++k) \
;         acc[ai][bj][m][n] = __builtin_amdgcn_mfma_f32_16x16x32_bf16(Bt[n][k], At[m][k], acc[ai][bj][m][n], 0, 0, 0); __builtin_amdgcn_s_setprio(0); } while (0)
; #define PG8_WAIT_L(n) asm volatile("s_waitcnt lgkmcnt(" #n ")" ::: "memory")
; #define PG8_BAR __builtin_amdgcn_s_barrier()
; #define PG8_SCHED __builtin_amdgcn_sched_barrier(0)
; template <class Epi>
; __device__ __forceinline__ void gemm_phase(LAS unsigned char* lds, const Gemm g, const StaticOrder& S, const Epi& E) {
;     ...
;         const bool has_next = S.next(ui + 1, nxt);
;         const char* nA = has_next ? (const char*)g.A + (size_t)nxt.pm * tstepA + (size_t)nxt.kt0 * kstep : cA; const char* nB = has_next ? (const char*)g.Bt + (size_t)nxt.pn * tstepB + (size_t)nxt.kt0 * kstep : cB;
;         const int nt = cur.nkt;
;         for (int t = 0; t < nt; t += 2) {
;             const bool last = (t == nt - 2);
;             const char* a1 = cA + (size_t)(t + 1) * kstep;
;             const char* a2 = last ? nA : cA + (size_t)(t + 2) * kstep; const char* b2 = last ? nB : cB + (size_t)(t + 2) * kstep;
;             const char* a3 = a2 + kstep; const char* b3 = b2 + kstep;
;             PG8_LDB(B0, 0, 0); PG8_SCHED; PG8_LDA(At, 0, 0); PG8_STAGE(PG8_SA(1, 1), a1 + hstepA, voffA);
;             PG8_WAIT_L(8); PG8_BAR; PG8_WAIT_L(0); PG8_MMA(0, 0, At, B0); PG8_BAR; PG8_SCHED;
.LBB0_909:
	s_add_i32 s18, s81, -2
	s_add_u32 s46, s46, 0x160080
	s_addc_u32 s47, s47, 0
	s_add_u32 s41, s54, 0x100
	s_addc_u32 s82, s55, 0
	s_mov_b32 s54, 0
	s_add_i32 s83, s54, 2
	s_add_u32 s55, s46, 0xffea0080
	s_addc_u32 s56, s47, -1
	s_cmp_eq_u32 s18, s54
	s_cselect_b32 s54, s0, s41
	s_cselect_b32 s57, s45, s56
	s_cselect_b32 s56, s44, s55
	s_cselect_b32 s55, s1, s82
	ds_read_b128 v[150:153], v170
	ds_read_b128 v[154:157], v170 offset:1024
	ds_read_b128 v[174:177], v170 offset:2048
	ds_read_b128 v[178:181], v170 offset:3072
	ds_read_b128 v[182:185], v171
	ds_read_b128 v[186:189], v171 offset:1024
	ds_read_b128 v[190:193], v171 offset:2048
	ds_read_b128 v[194:197], v171 offset:3072
	ds_read_b128 v[198:201], v171 offset:4096
	ds_read_b128 v[202:205], v171 offset:5120
	ds_read_b128 v[206:209], v171 offset:6144
	ds_read_b128 v[210:213], v171 offset:7168
	ds_read_b128 v[214:217], v172
	ds_read_b128 v[218:221], v172 offset:1024
	ds_read_b128 v[222:225], v172 offset:2048
	ds_read_b128 v[226:229], v172 offset:3072
	s_add_i32 m0, s33, 0xc000
	v_lshl_add_u64 v[158:159], s[46:47], 0, v[144:145]
	global_load_lds_dwordx4 v[158:159], off
	s_add_i32 m0, s33, 0xe000
	v_lshl_add_u64 v[158:159], s[46:47], 0, v[146:147]
	global_load_lds_dwordx4 v[158:159], off
	s_cmp_eq_u32 s99, 0
	s_cbranch_scc1 .Lrw3_0s
	s_waitcnt vmcnt(24) lgkmcnt(0)
	s_branch .Lrw3_0d

; #define PG8_STAGE(bufoff, gbase, voff) do { _Pragma("unroll") for (int _i = 0; _i < 2; ++_i) \
;         __builtin_amdgcn_global_load_lds((const unsigned*)((const char*)(gbase) + (voff)[_i]), (LAS unsigned*)(lds + (bufoff) + ldsw + _i * 8192), 16, 0, 0); } while (0)
; #define PG8_LDA(dst, b, h) do { _Pragma("unroll") for (int m = 0; m < 4; ++m) _Pragma("unroll") for (int k = 0; k < 2; ++k) dst[m][k] = *(const LAS bf16x8*)(lds + PG8_SA(b, h) + aoff + m * 2048 + k * 1024); } while (0)
; #define PG8_LDB(dst, b, h) do { _Pragma("unroll") for (int n = 0; n < 2; ++n) _Pragma("unroll") for (int k = 0; k < 2; ++k) dst[n][k] = *(const LAS bf16x8*)(lds + PG8_SB(b, h) + boff + n * 2048 + k * 1024); } while (0)
; #define PG8_MMA(ai, bj, At, Bt) do { __builtin_amdgcn_s_setprio(1); _Pragma("unroll") for (int m = 0; m < 4; ++m) _Pragma("unroll") for (int n = 0; n < 2; ++n) _Pragma("unroll") for (int k = 0; k < 2; ++k) \
;         acc[ai][bj][m][n] = __builtin_amdgcn_mfma_f32_16x16x32_bf16(Bt[n][k], At[m][k], acc[ai][bj][m][n], 0, 0, 0); __builtin_amdgcn_s_setprio(0); } while (0)
; #define PG8_WAIT_L(n) asm volatile("s_waitcnt lgkmcnt(" #n ")" ::: "memory")
; #define PG8_BAR __builtin_amdgcn_s_barrier()
; #define PG8_SCHED __builtin_amdgcn_sched_barrier(0)
; template <class Epi>
; __device__ __forceinline__ void gemm_phase(LAS unsigned char* lds, const Gemm g, const StaticOrder& S, const Epi& E) {
;     ...
;             PG8_LDB(B0, 0, 0); PG8_SCHED; PG8_LDA(At, 0, 0); PG8_STAGE(PG8_SA(1, 1), a1 + hstepA, voffA);
;             PG8_WAIT_L(8); PG8_BAR; PG8_WAIT_L(0); PG8_MMA(0, 0, At, B0); PG8_BAR; PG8_SCHED;
;             PG8_LDB(B1, 0, 1); PG8_STAGE(PG8_SB(0, 0), b2, voffB);
;             PG8_BAR; PG8_WAIT_L(0); PG8_MMA(0, 1, At, B1); PG8_BAR;
;             PG8_LDA(At, 0, 1); PG8_STAGE(PG8_SA(0, 0), a2, voffA);
;             PG8_BAR; PG8_WAIT_L(0); PG8_MMA(1, 0, At, B0); PG8_BAR; PG8_SCHED;
.Lrw3_0d:
	s_barrier
	v_mfma_f32_16x16x32_bf16 v[124:127], v[150:153], v[182:185], 0
	v_mfma_f32_16x16x32_bf16 v[120:123], v[174:177], v[182:185], 0
	v_mfma_f32_16x16x32_bf16 v[116:119], v[150:153], v[190:193], 0
	v_mfma_f32_16x16x32_bf16 v[108:111], v[174:177], v[190:193], 0
	v_mfma_f32_16x16x32_bf16 v[100:103], v[150:153], v[198:201], 0
	v_mfma_f32_16x16x32_bf16 v[92:95], v[174:177], v[198:201], 0
	v_mfma_f32_16x16x32_bf16 v[84:87], v[150:153], v[206:209], 0
	v_mfma_f32_16x16x32_bf16 v[76:79], v[174:177], v[206:209], 0
	v_mfma_f32_16x16x32_bf16 v[124:127], v[154:157], v[186:189], v[124:127]
	v_mfma_f32_16x16x32_bf16 v[120:123], v[178:181], v[186:189], v[120:123]
	v_mfma_f32_16x16x32_bf16 v[116:119], v[154:157], v[194:197], v[116:119]
	v_mfma_f32_16x16x32_bf16 v[108:111], v[178:181], v[194:197], v[108:111]
	v_mfma_f32_16x16x32_bf16 v[100:103], v[154:157], v[202:205], v[100:103]
	v_mfma_f32_16x16x32_bf16 v[92:95], v[178:181], v[202:205], v[92:95]
	v_mfma_f32_16x16x32_bf16 v[84:87], v[154:157], v[210:213], v[84:87]
	v_mfma_f32_16x16x32_bf16 v[76:79], v[178:181], v[210:213], v[76:79]
	v_mfma_f32_16x16x32_bf16 v[112:115], v[214:217], v[182:185], 0
	v_mfma_f32_16x16x32_bf16 v[104:107], v[222:225], v[182:185], 0
	v_mfma_f32_16x16x32_bf16 v[96:99], v[214:217], v[190:193], 0
	v_mfma_f32_16x16x32_bf16 v[88:91], v[222:225], v[190:193], 0
	v_mfma_f32_16x16x32_bf16 v[80:83], v[214:217], v[198:201], 0
	v_mfma_f32_16x16x32_bf16 v[72:75], v[222:225], v[198:201], 0
	v_mfma_f32_16x16x32_bf16 v[68:71], v[214:217], v[206:209], 0
	v_mfma_f32_16x16x32_bf16 v[64:67], v[222:225], v[206:209], 0
	v_mfma_f32_16x16x32_bf16 v[112:115], v[218:221], v[186:189], v[112:115]
	v_mfma_f32_16x16x32_bf16 v[104:107], v[226:229], v[186:189], v[104:107]
	v_mfma_f32_16x16x32_bf16 v[96:99], v[218:221], v[194:197], v[96:99]
	v_mfma_f32_16x16x32_bf16 v[88:91], v[226:229], v[194:197], v[88:91]
	v_mfma_f32_16x16x32_bf16 v[80:83], v[218:221], v[202:205], v[80:83]
	v_mfma_f32_16x16x32_bf16 v[72:75], v[226:229], v[202:205], v[72:75]
	v_mfma_f32_16x16x32_bf16 v[68:71], v[218:221], v[210:213], v[68:71]
	v_mfma_f32_16x16x32_bf16 v[64:67], v[226:229], v[210:213], v[64:67]
	s_barrier
	ds_read_b128 v[182:185], v171 offset:16384
	ds_read_b128 v[186:189], v171 offset:17408
	ds_read_b128 v[190:193], v171 offset:18432
	ds_read_b128 v[194:197], v171 offset:19456
	ds_read_b128 v[198:201], v171 offset:20480
	ds_read_b128 v[202:205], v171 offset:21504
	ds_read_b128 v[206:209], v171 offset:22528
	ds_read_b128 v[210:213], v171 offset:23552
	s_add_i32 s84, s65, s21
	s_mov_b32 m0, s84
	v_lshl_add_u64 v[158:159], s[54:55], 0, v[138:139]
	global_load_lds_dwordx4 v[158:159], off
	s_add_i32 m0, s84, 0x2000
	v_lshl_add_u64 v[230:231], s[54:55], 0, v[142:143]
	global_load_lds_dwordx4 v[230:231], off
	s_mov_b32 m0, s33
	v_lshl_add_u64 v[232:233], s[56:57], 0, v[136:137]
	global_load_lds_dwordx4 v[232:233], off
	s_mov_b32 m0, s35
	v_lshl_add_u64 v[234:235], s[56:57], 0, v[140:141]
	global_load_lds_dwordx4 v[234:235], off
	s_add_u32 s84, s54, 0xb0000
	s_addc_u32 s85, s55, 0
	s_add_i32 s86, s66, s21
	s_mov_b32 m0, s86
	v_lshl_add_u64 v[240:241], s[84:85], 0, v[138:139]
	global_load_lds_dwordx4 v[240:241], off
	s_add_i32 m0, s86, 0x2000
	v_lshl_add_u64 v[240:241], s[84:85], 0, v[142:143]
	global_load_lds_dwordx4 v[240:241], off
	s_cmp_eq_u32 s99, 0
	s_cbranch_scc1 .Lrw3_1s
	s_waitcnt vmcnt(24) lgkmcnt(0)
	s_branch .Lrw3_1d

; #define PG8_STAGE(bufoff, gbase, voff) do { _Pragma("unroll") for (int _i = 0; _i < 2; ++_i) \
;         __builtin_amdgcn_global_load_lds((const unsigned*)((const char*)(gbase) + (voff)[_i]), (LAS unsigned*)(lds + (bufoff) + ldsw + _i * 8192), 16, 0, 0); } while (0)
; #define PG8_LDA(dst, b, h) do { _Pragma("unroll") for (int m = 0; m < 4; ++m) _Pragma("unroll") for (int k = 0; k < 2; ++k) dst[m][k] = *(const LAS bf16x8*)(lds + PG8_SA(b, h) + aoff + m * 2048 + k * 1024); } while (0)
; #define PG8_LDB(dst, b, h) do { _Pragma("unroll") for (int n = 0; n < 2; ++n) _Pragma("unroll") for (int k = 0; k < 2; ++k) dst[n][k] = *(const LAS bf16x8*)(lds + PG8_SB(b, h) + boff + n * 2048 + k * 1024); } while (0)
; #define PG8_MMA(ai, bj, At, Bt) do { __builtin_amdgcn_s_setprio(1); _Pragma("unroll") for (int m = 0; m < 4; ++m) _Pragma("unroll") for (int n = 0; n < 2; ++n) _Pragma("unroll") for (int k = 0; k < 2; ++k) \
;         acc[ai][bj][m][n] = __builtin_amdgcn_mfma_f32_16x16x32_bf16(Bt[n][k], At[m][k], acc[ai][bj][m][n], 0, 0, 0); __builtin_amdgcn_s_setprio(0); } while (0)
; #define PG8_WAIT_V(n) asm volatile("s_waitcnt vmcnt(" #n ")" ::: "memory")
; #define PG8_WAIT_L(n) asm volatile("s_waitcnt lgkmcnt(" #n ")" ::: "memory")
; #define PG8_BAR __builtin_amdgcn_s_barrier()
; #define PG8_SCHED __builtin_amdgcn_sched_barrier(0)
; template <class Epi>
; __device__ __forceinline__ void gemm_phase(LAS unsigned char* lds, const Gemm g, const StaticOrder& S, const Epi& E) {
;     ...
;             PG8_BAR; PG8_WAIT_L(0); PG8_MMA(0, 1, At, B1); PG8_BAR;
;             PG8_LDA(At, 0, 1); PG8_STAGE(PG8_SA(0, 0), a2, voffA);
;             PG8_BAR; PG8_WAIT_L(0); PG8_MMA(1, 0, At, B0); PG8_BAR; PG8_SCHED;
;             PG8_STAGE(PG8_SB(0, 1), b2 + hstepB, voffB);
;             PG8_WAIT_V(6); PG8_BAR; PG8_MMA(1, 1, At, B1); PG8_BAR;
;             PG8_LDB(B0, 1, 0); PG8_SCHED; PG8_LDA(At, 1, 0); PG8_STAGE(PG8_SA(0, 1), a2 + hstepA, voffA);
;             PG8_WAIT_L(8); PG8_BAR; PG8_WAIT_L(0); PG8_MMA(0, 0, At, B0); PG8_BAR; PG8_SCHED;
.Lrw3_1d:
	s_mov_b32 s99, 1
	s_barrier
	v_mfma_f32_16x16x32_bf16 v[60:63], v[150:153], v[182:185], 0
	v_mfma_f32_16x16x32_bf16 v[56:59], v[174:177], v[182:185], 0
	v_mfma_f32_16x16x32_bf16 v[52:55], v[150:153], v[190:193], 0
	v_mfma_f32_16x16x32_bf16 v[44:47], v[174:177], v[190:193], 0
	v_mfma_f32_16x16x32_bf16 v[36:39], v[150:153], v[198:201], 0
	v_mfma_f32_16x16x32_bf16 v[28:31], v[174:177], v[198:201], 0
	v_mfma_f32_16x16x32_bf16 v[20:23], v[150:153], v[206:209], 0
	v_mfma_f32_16x16x32_bf16 v[12:15], v[174:177], v[206:209], 0
	v_mfma_f32_16x16x32_bf16 v[60:63], v[154:157], v[186:189], v[60:63]
	v_mfma_f32_16x16x32_bf16 v[56:59], v[178:181], v[186:189], v[56:59]
	v_mfma_f32_16x16x32_bf16 v[52:55], v[154:157], v[194:197], v[52:55]
	v_mfma_f32_16x16x32_bf16 v[44:47], v[178:181], v[194:197], v[44:47]
	v_mfma_f32_16x16x32_bf16 v[36:39], v[154:157], v[202:205], v[36:39]
	v_mfma_f32_16x16x32_bf16 v[28:31], v[178:181], v[202:205], v[28:31]
	v_mfma_f32_16x16x32_bf16 v[20:23], v[154:157], v[210:213], v[20:23]
	v_mfma_f32_16x16x32_bf16 v[12:15], v[178:181], v[210:213], v[12:15]
	v_mfma_f32_16x16x32_bf16 v[48:51], v[214:217], v[182:185], 0
	v_mfma_f32_16x16x32_bf16 v[40:43], v[222:225], v[182:185], 0
	v_mfma_f32_16x16x32_bf16 v[32:35], v[214:217], v[190:193], 0
	v_mfma_f32_16x16x32_bf16 v[24:27], v[222:225], v[190:193], 0
	v_mfma_f32_16x16x32_bf16 v[16:19], v[214:217], v[198:201], 0
	v_mfma_f32_16x16x32_bf16 v[8:11], v[222:225], v[198:201], 0
	v_mfma_f32_16x16x32_bf16 v[4:7], v[214:217], v[206:209], 0
	v_mfma_f32_16x16x32_bf16 v[0:3], v[222:225], v[206:209], 0
	v_mfma_f32_16x16x32_bf16 v[48:51], v[218:221], v[186:189], v[48:51]
	v_mfma_f32_16x16x32_bf16 v[40:43], v[226:229], v[186:189], v[40:43]
	v_mfma_f32_16x16x32_bf16 v[32:35], v[218:221], v[194:197], v[32:35]
	v_mfma_f32_16x16x32_bf16 v[24:27], v[226:229], v[194:197], v[24:27]
	v_mfma_f32_16x16x32_bf16 v[16:19], v[218:221], v[202:205], v[16:19]
	v_mfma_f32_16x16x32_bf16 v[8:11], v[226:229], v[202:205], v[8:11]
	v_mfma_f32_16x16x32_bf16 v[4:7], v[218:221], v[210:213], v[4:7]
	v_mfma_f32_16x16x32_bf16 v[0:3], v[226:229], v[210:213], v[0:3]
	s_barrier
	s_add_i32 s84, 0, 0x18000
	v_add_u32_e32 v173, s84, v168
	ds_read_b128 v[150:153], v173
	ds_read_b128 v[154:157], v173 offset:1024
	ds_read_b128 v[174:177], v173 offset:2048
	ds_read_b128 v[178:181], v173 offset:3072
	ds_read_b128 v[182:185], v171 offset:32768
	ds_read_b128 v[186:189], v171 offset:33792
	ds_read_b128 v[190:193], v171 offset:34816
	ds_read_b128 v[194:197], v171 offset:35840
	ds_read_b128 v[198:201], v171 offset:36864
	ds_read_b128 v[202:205], v171 offset:37888
	ds_read_b128 v[206:209], v171 offset:38912
	ds_read_b128 v[210:213], v171 offset:39936
	s_add_i32 s98, 0, 0x1c000
	v_add_u32_e32 v246, s98, v168
	ds_read_b128 v[214:217], v246
	ds_read_b128 v[218:221], v246 offset:1024
	ds_read_b128 v[222:225], v246 offset:2048
	ds_read_b128 v[226:229], v246 offset:3072
	s_add_u32 s56, s56, 0x160000
	s_addc_u32 s57, s57, 0
	s_mov_b32 m0, s58
	v_lshl_add_u64 v[244:245], s[56:57], 0, v[136:137]
	global_load_lds_dwordx4 v[244:245], off
	s_mov_b32 m0, s59
	v_lshl_add_u64 v[244:245], s[56:57], 0, v[140:141]
	global_load_lds_dwordx4 v[244:245], off
	s_waitcnt vmcnt(8) lgkmcnt(0)
	s_barrier
	v_mfma_f32_16x16x32_bf16 v[124:127], v[150:153], v[182:185], v[124:127]
	v_mfma_f32_16x16x32_bf16 v[120:123], v[174:177], v[182:185], v[120:123]
	v_mfma_f32_16x16x32_bf16 v[116:119], v[150:153], v[190:193], v[116:119]
	v_mfma_f32_16x16x32_bf16 v[108:111], v[174:177], v[190:193], v[108:111]
	v_mfma_f32_16x16x32_bf16 v[100:103], v[150:153], v[198:201], v[100:103]
	v_mfma_f32_16x16x32_bf16 v[92:95], v[174:177], v[198:201], v[92:95]
	v_mfma_f32_16x16x32_bf16 v[84:87], v[150:153], v[206:209], v[84:87]
	v_mfma_f32_16x16x32_bf16 v[76:79], v[174:177], v[206:209], v[76:79]
	v_mfma_f32_16x16x32_bf16 v[124:127], v[154:157], v[186:189], v[124:127]
	v_mfma_f32_16x16x32_bf16 v[120:123], v[178:181], v[186:189], v[120:123]
	v_mfma_f32_16x16x32_bf16 v[116:119], v[154:157], v[194:197], v[116:119]
	v_mfma_f32_16x16x32_bf16 v[108:111], v[178:181], v[194:197], v[108:111]
	v_mfma_f32_16x16x32_bf16 v[100:103], v[154:157], v[202:205], v[100:103]
	v_mfma_f32_16x16x32_bf16 v[92:95], v[178:181], v[202:205], v[92:95]
	v_mfma_f32_16x16x32_bf16 v[84:87], v[154:157], v[210:213], v[84:87]
	v_mfma_f32_16x16x32_bf16 v[76:79], v[178:181], v[210:213], v[76:79]
	v_mfma_f32_16x16x32_bf16 v[112:115], v[214:217], v[182:185], v[112:115]
	v_mfma_f32_16x16x32_bf16 v[104:107], v[222:225], v[182:185], v[104:107]
	v_mfma_f32_16x16x32_bf16 v[96:99], v[214:217], v[190:193], v[96:99]
	v_mfma_f32_16x16x32_bf16 v[88:91], v[222:225], v[190:193], v[88:91]
	v_mfma_f32_16x16x32_bf16 v[80:83], v[214:217], v[198:201], v[80:83]
	v_mfma_f32_16x16x32_bf16 v[72:75], v[222:225], v[198:201], v[72:75]
	v_mfma_f32_16x16x32_bf16 v[68:71], v[214:217], v[206:209], v[68:71]
	v_mfma_f32_16x16x32_bf16 v[64:67], v[222:225], v[206:209], v[64:67]
	v_mfma_f32_16x16x32_bf16 v[112:115], v[218:221], v[186:189], v[112:115]
	v_mfma_f32_16x16x32_bf16 v[104:107], v[226:229], v[186:189], v[104:107]
	v_mfma_f32_16x16x32_bf16 v[96:99], v[218:221], v[194:197], v[96:99]
	v_mfma_f32_16x16x32_bf16 v[88:91], v[226:229], v[194:197], v[88:91]
	v_mfma_f32_16x16x32_bf16 v[80:83], v[218:221], v[202:205], v[80:83]
	v_mfma_f32_16x16x32_bf16 v[72:75], v[226:229], v[202:205], v[72:75]
	v_mfma_f32_16x16x32_bf16 v[68:71], v[218:221], v[210:213], v[68:71]
	v_mfma_f32_16x16x32_bf16 v[64:67], v[226:229], v[210:213], v[64:67]
	s_barrier
; #define PG8_STAGE(bufoff, gbase, voff) do { _Pragma("unroll") for (int _i = 0; _i < 2; ++_i) \
;         __builtin_amdgcn_global_load_lds((const unsigned*)((const char*)(gbase) + (voff)[_i]), (LAS unsigned*)(lds + (bufoff) + ldsw + _i * 8192), 16, 0, 0); } while (0)
; #define PG8_LDA(dst, b, h) do { _Pragma("unroll") for (int m = 0; m < 4; ++m) _Pragma("unroll") for (int k = 0; k < 2; ++k) dst[m][k] = *(const LAS bf16x8*)(lds + PG8_SA(b, h) + aoff + m * 2048 + k * 1024); } while (0)
; #define PG8_LDB(dst, b, h) do { _Pragma("unroll") for (int n = 0; n < 2; ++n) _Pragma("unroll") for (int k = 0; k < 2; ++k) dst[n][k] = *(const LAS bf16x8*)(lds + PG8_SB(b, h) + boff + n * 2048 + k * 1024); } while (0)
; #define PG8_MMA(ai, bj, At, Bt) do { __builtin_amdgcn_s_setprio(1); _Pragma("unroll") for (int m = 0; m < 4; ++m) _Pragma("unroll") for (int n = 0; n < 2; ++n) _Pragma("unroll") for (int k = 0; k < 2; ++k) \
;         acc[ai][bj][m][n] = __builtin_amdgcn_mfma_f32_16x16x32_bf16(Bt[n][k], At[m][k], acc[ai][bj][m][n], 0, 0, 0); __builtin_amdgcn_s_setprio(0); } while (0)
; #define PG8_WAIT_V(n) asm volatile("s_waitcnt vmcnt(" #n ")" ::: "memory")
; #define PG8_WAIT_L(n) asm volatile("s_waitcnt lgkmcnt(" #n ")" ::: "memory")
; #define PG8_BAR __builtin_amdgcn_s_barrier()
; #define PG8_SCHED __builtin_amdgcn_sched_barrier(0)
; template <class Epi>
; __device__ __forceinline__ void gemm_phase(LAS unsigned char* lds, const Gemm g, const StaticOrder& S, const Epi& E) {
;     ...
;             PG8_LDB(B1, 1, 1); PG8_STAGE(PG8_SB(1, 0), b3, voffB);
;             PG8_BAR; PG8_WAIT_L(0); PG8_MMA(0, 1, At, B1); PG8_BAR;
;             PG8_LDA(At, 1, 1); PG8_STAGE(PG8_SA(1, 0), a3, voffA);
;             PG8_BAR; PG8_WAIT_L(0); PG8_MMA(1, 0, At, B0); PG8_BAR; PG8_SCHED;
;             PG8_STAGE(PG8_SB(1, 1), b3 + hstepB, voffB);
;             PG8_WAIT_V(6); PG8_BAR; PG8_MMA(1, 1, At, B1); PG8_BAR;
	ds_read_b128 v[182:185], v171 offset:49152
	ds_read_b128 v[186:189], v171 offset:50176
	ds_read_b128 v[190:193], v171 offset:51200
	ds_read_b128 v[194:197], v171 offset:52224
	ds_read_b128 v[198:201], v171 offset:53248
	ds_read_b128 v[202:205], v171 offset:54272
	ds_read_b128 v[206:209], v171 offset:55296
	ds_read_b128 v[210:213], v171 offset:56320
	s_add_i32 s57, s84, s21
	s_mov_b32 m0, s57
	v_lshl_add_u64 v[158:159], v[158:159], 0, s[22:23]
	global_load_lds_dwordx4 v[158:159], off
	s_add_i32 m0, s57, 0x2000
	v_lshl_add_u64 v[158:159], v[230:231], 0, s[22:23]
	global_load_lds_dwordx4 v[158:159], off
	s_mov_b32 m0, s60
	v_lshl_add_u64 v[158:159], v[232:233], 0, s[22:23]
	global_load_lds_dwordx4 v[158:159], off
	s_mov_b32 m0, s61
	v_lshl_add_u64 v[158:159], v[234:235], 0, s[22:23]
	global_load_lds_dwordx4 v[158:159], off
	s_add_u32 s54, s54, 0xb0080
	s_addc_u32 s55, s55, 0
	s_add_i32 s56, s98, s21
	s_mov_b32 m0, s56
	v_lshl_add_u64 v[240:241], s[54:55], 0, v[138:139]
	global_load_lds_dwordx4 v[240:241], off
	s_add_i32 m0, s56, 0x2000
	v_lshl_add_u64 v[240:241], s[54:55], 0, v[142:143]
	global_load_lds_dwordx4 v[240:241], off
	s_waitcnt vmcnt(8) lgkmcnt(0)
	s_barrier
	v_mfma_f32_16x16x32_bf16 v[60:63], v[150:153], v[182:185], v[60:63]
	v_mfma_f32_16x16x32_bf16 v[56:59], v[174:177], v[182:185], v[56:59]
	v_mfma_f32_16x16x32_bf16 v[52:55], v[150:153], v[190:193], v[52:55]
	v_mfma_f32_16x16x32_bf16 v[44:47], v[174:177], v[190:193], v[44:47]
	v_mfma_f32_16x16x32_bf16 v[36:39], v[150:153], v[198:201], v[36:39]
	v_mfma_f32_16x16x32_bf16 v[28:31], v[174:177], v[198:201], v[28:31]
	v_mfma_f32_16x16x32_bf16 v[20:23], v[150:153], v[206:209], v[20:23]
	v_mfma_f32_16x16x32_bf16 v[12:15], v[174:177], v[206:209], v[12:15]
	v_mfma_f32_16x16x32_bf16 v[60:63], v[154:157], v[186:189], v[60:63]
	v_mfma_f32_16x16x32_bf16 v[56:59], v[178:181], v[186:189], v[56:59]
	v_mfma_f32_16x16x32_bf16 v[52:55], v[154:157], v[194:197], v[52:55]
	v_mfma_f32_16x16x32_bf16 v[44:47], v[178:181], v[194:197], v[44:47]
	v_mfma_f32_16x16x32_bf16 v[36:39], v[154:157], v[202:205], v[36:39]
	v_mfma_f32_16x16x32_bf16 v[28:31], v[178:181], v[202:205], v[28:31]
	v_mfma_f32_16x16x32_bf16 v[20:23], v[154:157], v[210:213], v[20:23]
	v_mfma_f32_16x16x32_bf16 v[12:15], v[178:181], v[210:213], v[12:15]
	v_mfma_f32_16x16x32_bf16 v[48:51], v[214:217], v[182:185], v[48:51]
	v_mfma_f32_16x16x32_bf16 v[40:43], v[222:225], v[182:185], v[40:43]
	v_mfma_f32_16x16x32_bf16 v[32:35], v[214:217], v[190:193], v[32:35]
	v_mfma_f32_16x16x32_bf16 v[24:27], v[222:225], v[190:193], v[24:27]
	v_mfma_f32_16x16x32_bf16 v[16:19], v[214:217], v[198:201], v[16:19]
	v_mfma_f32_16x16x32_bf16 v[8:11], v[222:225], v[198:201], v[8:11]
	v_mfma_f32_16x16x32_bf16 v[4:7], v[214:217], v[206:209], v[4:7]
	v_mfma_f32_16x16x32_bf16 v[0:3], v[222:225], v[206:209], v[0:3]
	v_mfma_f32_16x16x32_bf16 v[48:51], v[218:221], v[186:189], v[48:51]
	v_mfma_f32_16x16x32_bf16 v[40:43], v[226:229], v[186:189], v[40:43]
	v_mfma_f32_16x16x32_bf16 v[32:35], v[218:221], v[194:197], v[32:35]
	v_mfma_f32_16x16x32_bf16 v[24:27], v[226:229], v[194:197], v[24:27]
	v_mfma_f32_16x16x32_bf16 v[16:19], v[218:221], v[202:205], v[16:19]
	v_mfma_f32_16x16x32_bf16 v[8:11], v[226:229], v[202:205], v[8:11]
	v_mfma_f32_16x16x32_bf16 v[4:7], v[218:221], v[210:213], v[4:7]
	v_mfma_f32_16x16x32_bf16 v[0:3], v[226:229], v[210:213], v[0:3]
	s_add_u32 s46, s46, 0x100
	s_addc_u32 s47, s47, 0
	s_add_u32 s41, s41, 0x100
	s_addc_u32 s82, s82, 0
	s_cmp_ge_i32 s83, s81
	s_mov_b32 s54, s83
	s_barrier

; #define PG8_STAGE(bufoff, gbase, voff) do { _Pragma("unroll") for (int _i = 0; _i < 2; ++_i) \
;         __builtin_amdgcn_global_load_lds((const unsigned*)((const char*)(gbase) + (voff)[_i]), (LAS unsigned*)(lds + (bufoff) + ldsw + _i * 8192), 16, 0, 0); } while (0)
; #define PG8_WAIT_V(n) asm volatile("s_waitcnt vmcnt(" #n ")" ::: "memory")
; #define PG8_BAR __builtin_amdgcn_s_barrier()
; template <class Epi>
; __device__ __forceinline__ void gemm_phase(LAS unsigned char* lds, const Gemm g, const StaticOrder& S, const Epi& E) {
;     ...
;     for (int i = 0; i < 2; ++i) { int R, C; stage_rc(tid * 16 + i * 8192, R, C); const int Rb = Epi::PERM ? ((R & ~31) + perm32(R & 31)) : R;
;         voffA[i] = (unsigned)(R * lda + C) * 2u; voffB[i] = (unsigned)(Rb * K + C) * 2u; }
;     const size_t kstep = (size_t)(BK * 2);
;     const size_t hstepA = (size_t)HALF * lda * 2, hstepB = (size_t)HALF * K * 2;
;     const size_t tstepA = 2 * hstepA, tstepB = 2 * hstepB;
;     const unsigned ldsw = (unsigned)wid * 1024u;
;     const int aoff = lds_byte(wr * 64 + fr, fq * 8), boff = lds_byte(wc * 32 + fr, fq * 8);
;     ...
;     Unit cur, nxt; int ui = 0;
;     if (!S.next(0, cur)) return;
;     f32x4 acc[2][2][4][2];
; #pragma unroll
;     for (int a = 0; a < 2; ++a)
; #pragma unroll
;         for (int b = 0; b < 2; ++b)
; #pragma unroll
;             for (int m = 0; m < 4; ++m)
; #pragma unroll
;                 for (int n = 0; n < 2; ++n) acc[a][b][m][n] = (f32x4){0.f, 0.f, 0.f, 0.f};
;     bf16x8 At[4][2], B0[2][2], B1[2][2];
;     const char* cA = (const char*)g.A + (size_t)cur.pm * tstepA + (size_t)cur.kt0 * kstep; const char* cB = (const char*)g.Bt + (size_t)cur.pn * tstepB + (size_t)cur.kt0 * kstep;
;     PG8_STAGE(PG8_SB(0, 0), cB, voffB); PG8_STAGE(PG8_SA(0, 0), cA, voffA); PG8_STAGE(PG8_SB(0, 1), cB + hstepB, voffB); PG8_STAGE(PG8_SA(0, 1), cA + hstepA, voffA);
;     if (wr == 1) PG8_BAR;
;     PG8_WAIT_V(4); PG8_BAR;
;     PG8_STAGE(PG8_SB(1, 0), cB + kstep, voffB); PG8_STAGE(PG8_SA(1, 0), cA + kstep, voffA); PG8_STAGE(PG8_SB(1, 1), cB + hstepB + kstep, voffB);
;     PG8_WAIT_V(6); PG8_BAR;
.LBB0_1129:
	s_add_u32 s10, s92, 0x4301e00
	s_addc_u32 s11, s93, 0
	s_lshl_b32 s0, s12, 5
	s_mov_b64 s[12:13], 0x80
	s_and_b32 s24, s0, 0x60
	s_add_i32 m0, s33, 0x18000
	v_lshl_add_u64 v[6:7], v[6:7], 0, s[12:13]
	s_lshl_b32 s23, s22, 13
	s_lshl_b32 s25, s24, 7
	s_waitcnt vmcnt(0)
	s_barrier
	global_load_lds_dwordx4 v[6:7], off
	v_lshl_add_u64 v[4:5], v[4:5], 0, s[12:13]
	s_add_i32 m0, s33, 0x1a000
	s_add_i32 s60, s33, 0x8000
	s_add_i32 s61, s33, 0xa000
	global_load_lds_dwordx4 v[4:5], off
	v_lshl_add_u64 v[2:3], v[2:3], 0, s[12:13]
	s_mov_b32 m0, s60
	s_add_u32 s0, s54, 0x40080
	global_load_lds_dwordx4 v[2:3], off
	v_lshl_add_u64 v[0:1], v[0:1], 0, s[12:13]
	s_mov_b32 m0, s61
	s_addc_u32 s1, s55, 0
	global_load_lds_dwordx4 v[0:1], off
	s_add_i32 m0, s33, 0x1c000
	v_lshl_add_u64 v[0:1], s[0:1], 0, v[138:139]
	global_load_lds_dwordx4 v[0:1], off
	v_lshl_add_u64 v[0:1], s[0:1], 0, v[142:143]
	s_add_i32 m0, s33, 0x1e000
	v_lshlrev_b32_e32 v2, 2, v129
	global_load_lds_dwordx4 v[0:1], off
	v_and_b32_e32 v0, 15, v129
	v_lshlrev_b32_e32 v1, 1, v11
	v_lshlrev_b32_e32 v3, 6, v129
	s_movk_i32 s0, 0x3c0
	v_lshl_or_b32 v133, s22, 6, v0
	v_lshl_or_b32 v0, v0, 6, v1
	v_and_b32_e32 v2, 32, v2
	v_and_or_b32 v1, v3, s0, v1
	v_bitop3_b32 v135, s25, v1, v2 bitop3:0xf6
	v_lshlrev_b32_e32 v1, 8, v129
	v_bitop3_b32 v0, v0, s23, v2 bitop3:0xde
	v_and_b32_e32 v1, 0x38000, v1
	v_lshlrev_b32_e32 v2, 11, v10
	v_or3_b32 v1, v8, v1, v2
	v_add_u32_e32 v144, v1, v9
	v_lshlrev_b32_e32 v1, 4, v12
	s_waitcnt vmcnt(6)
	v_and_b32_e32 v1, 0x78000, v1
	v_or3_b32 v1, v8, v1, v2
	s_add_i32 s66, 0, 0x10000
	s_add_i32 s67, 0, 0x14000
	s_brev_b32 s22, 63
	s_ashr_i32 s62, s14, 31
	s_mov_b32 s63, s14
	s_ashr_i32 s65, s2, 31
	v_or_b32_e32 v162, s24, v11
	v_mov_b32_e32 v145, v139
	v_add_u32_e32 v146, v1, v9
	v_mov_b32_e32 v147, v139
	v_mov_b64_e32 v[148:149], 0xff
	v_add_u32_e32 v129, s66, v135
	v_add_u32_e32 v163, 0, v0
	v_add_u32_e32 v164, s67, v135
	s_mov_b32 s23, -1
	s_mov_b64 s[24:25], 0x80000
	s_mov_b32 s68, 0x80000
	s_mov_b64 s[26:27], 0x90000
	s_mov_b32 s69, 0x90000
	s_mov_b64 s[28:29], 0xa0000
	s_mov_b32 s70, 0xa0000
	s_mov_b64 s[36:37], 0xb0000
	s_movk_i32 s71, 0x2c00
	s_mov_b32 s72, 0
	s_barrier
	s_mov_b32 s99, 0
	s_branch .LBB0_1132

; #define PG8_STAGE(bufoff, gbase, voff) do { _Pragma("unroll") for (int _i = 0; _i < 2; ++_i) \
;         __builtin_amdgcn_global_load_lds((const unsigned*)((const char*)(gbase) + (voff)[_i]), (LAS unsigned*)(lds + (bufoff) + ldsw + _i * 8192), 16, 0, 0); } while (0)
; #define PG8_LDA(dst, b, h) do { _Pragma("unroll") for (int m = 0; m < 4; ++m) _Pragma("unroll") for (int k = 0; k < 2; ++k) dst[m][k] = *(const LAS bf16x8*)(lds + PG8_SA(b, h) + aoff + m * 2048 + k * 1024); } while (0)
; #define PG8_LDB(dst, b, h) do { _Pragma("unroll") for (int n = 0; n < 2; ++n) _Pragma("unroll") for (int k = 0; k < 2; ++k) dst[n][k] = *(const LAS bf16x8*)(lds + PG8_SB(b, h) + boff + n * 2048 + k * 1024); } while (0)
; #define PG8_MMA(ai, bj, At, Bt) do { __builtin_amdgcn_s_setprio(1); _Pragma("unroll") for (int m = 0; m < 4; ++m) _Pragma("unroll") for (int n = 0; n < 2; ++n) _Pragma("unroll") for (int k = 0; k < 2; ++k) \
;         acc[ai][bj][m][n] = __builtin_amdgcn_mfma_f32_16x16x32_bf16(Bt[n][k], At[m][k], acc[ai][bj][m][n], 0, 0, 0); __builtin_amdgcn_s_setprio(0); } while (0)
; #define PG8_WAIT_L(n) asm volatile("s_waitcnt lgkmcnt(" #n ")" ::: "memory")
; #define PG8_BAR __builtin_amdgcn_s_barrier()
; #define PG8_SCHED __builtin_amdgcn_sched_barrier(0)
; template <class Epi>
; __device__ __forceinline__ void gemm_phase(LAS unsigned char* lds, const Gemm g, const StaticOrder& S, const Epi& E) {
;     ...
;         const bool has_next = S.next(ui + 1, nxt);
;         const char* nA = has_next ? (const char*)g.A + (size_t)nxt.pm * tstepA + (size_t)nxt.kt0 * kstep : cA; const char* nB = has_next ? (const char*)g.Bt + (size_t)nxt.pn * tstepB + (size_t)nxt.kt0 * kstep : cB;
;         const int nt = cur.nkt;
;         for (int t = 0; t < nt; t += 2) {
;             const bool last = (t == nt - 2);
;             const char* a1 = cA + (size_t)(t + 1) * kstep;
;             const char* a2 = last ? nA : cA + (size_t)(t + 2) * kstep; const char* b2 = last ? nB : cB + (size_t)(t + 2) * kstep;
;             const char* a3 = a2 + kstep; const char* b3 = b2 + kstep;
;             PG8_LDB(B0, 0, 0); PG8_SCHED; PG8_LDA(At, 0, 0); PG8_STAGE(PG8_SA(1, 1), a1 + hstepA, voffA);
;             PG8_WAIT_L(8); PG8_BAR; PG8_WAIT_L(0); PG8_MMA(0, 0, At, B0); PG8_BAR; PG8_SCHED;
.LBB0_1145:
	s_add_i32 s39, s76, -2
	s_add_u32 s50, s50, 0x40080
	s_addc_u32 s51, s51, 0
	s_add_u32 s41, s54, 0x100
	s_addc_u32 s43, s55, 0
	s_mov_b32 s45, 0
	s_add_i32 s77, s45, 2
	s_add_u32 s54, s50, 0xfffc0080
	s_addc_u32 s55, s51, -1
	s_cmp_eq_u32 s39, s45
	s_cselect_b32 s57, s49, s55
	s_cselect_b32 s56, s48, s54
	s_cselect_b32 s55, s1, s43
	s_cselect_b32 s54, s0, s41
	ds_read_b128 v[150:153], v129
	ds_read_b128 v[154:157], v129 offset:1024
	ds_read_b128 v[158:161], v129 offset:2048
	ds_read_b128 v[166:169], v129 offset:3072
	ds_read_b128 v[170:173], v163
	ds_read_b128 v[174:177], v163 offset:1024
	ds_read_b128 v[178:181], v163 offset:2048
	ds_read_b128 v[182:185], v163 offset:3072
	ds_read_b128 v[186:189], v163 offset:4096
	ds_read_b128 v[190:193], v163 offset:5120
	ds_read_b128 v[194:197], v163 offset:6144
	ds_read_b128 v[198:201], v163 offset:7168
	ds_read_b128 v[202:205], v164
	ds_read_b128 v[206:209], v164 offset:1024
	ds_read_b128 v[210:213], v164 offset:2048
	ds_read_b128 v[214:217], v164 offset:3072
	s_add_i32 m0, s33, 0xc000
	v_lshl_add_u64 v[242:243], s[50:51], 0, v[144:145]
	global_load_lds_dwordx4 v[242:243], off
	s_add_i32 m0, s33, 0xe000
	v_lshl_add_u64 v[242:243], s[50:51], 0, v[146:147]
	global_load_lds_dwordx4 v[242:243], off
	s_cmp_eq_u32 s99, 0
	s_cbranch_scc1 .Lrw4_0s
	s_waitcnt vmcnt(24) lgkmcnt(0)
	s_branch .Lrw4_0d

; #define PG8_STAGE(bufoff, gbase, voff) do { _Pragma("unroll") for (int _i = 0; _i < 2; ++_i) \
;         __builtin_amdgcn_global_load_lds((const unsigned*)((const char*)(gbase) + (voff)[_i]), (LAS unsigned*)(lds + (bufoff) + ldsw + _i * 8192), 16, 0, 0); } while (0)
; #define PG8_LDA(dst, b, h) do { _Pragma("unroll") for (int m = 0; m < 4; ++m) _Pragma("unroll") for (int k = 0; k < 2; ++k) dst[m][k] = *(const LAS bf16x8*)(lds + PG8_SA(b, h) + aoff + m * 2048 + k * 1024); } while (0)
; #define PG8_LDB(dst, b, h) do { _Pragma("unroll") for (int n = 0; n < 2; ++n) _Pragma("unroll") for (int k = 0; k < 2; ++k) dst[n][k] = *(const LAS bf16x8*)(lds + PG8_SB(b, h) + boff + n * 2048 + k * 1024); } while (0)
; #define PG8_MMA(ai, bj, At, Bt) do { __builtin_amdgcn_s_setprio(1); _Pragma("unroll") for (int m = 0; m < 4; ++m) _Pragma("unroll") for (int n = 0; n < 2; ++n) _Pragma("unroll") for (int k = 0; k < 2; ++k) \
;         acc[ai][bj][m][n] = __builtin_amdgcn_mfma_f32_16x16x32_bf16(Bt[n][k], At[m][k], acc[ai][bj][m][n], 0, 0, 0); __builtin_amdgcn_s_setprio(0); } while (0)
; #define PG8_WAIT_L(n) asm volatile("s_waitcnt lgkmcnt(" #n ")" ::: "memory")
; #define PG8_BAR __builtin_amdgcn_s_barrier()
; #define PG8_SCHED __builtin_amdgcn_sched_barrier(0)
; template <class Epi>
; __device__ __forceinline__ void gemm_phase(LAS unsigned char* lds, const Gemm g, const StaticOrder& S, const Epi& E) {
;     ...
;             PG8_LDB(B0, 0, 0); PG8_SCHED; PG8_LDA(At, 0, 0); PG8_STAGE(PG8_SA(1, 1), a1 + hstepA, voffA);
;             PG8_WAIT_L(8); PG8_BAR; PG8_WAIT_L(0); PG8_MMA(0, 0, At, B0); PG8_BAR; PG8_SCHED;
;             PG8_LDB(B1, 0, 1); PG8_STAGE(PG8_SB(0, 0), b2, voffB);
;             PG8_BAR; PG8_WAIT_L(0); PG8_MMA(0, 1, At, B1); PG8_BAR;
;             PG8_LDA(At, 0, 1); PG8_STAGE(PG8_SA(0, 0), a2, voffA);
;             PG8_BAR; PG8_WAIT_L(0); PG8_MMA(1, 0, At, B0); PG8_BAR; PG8_SCHED;
.Lrw4_0d:
	s_barrier
	v_mfma_f32_16x16x32_bf16 v[124:127], v[150:153], v[170:173], 0
	v_mfma_f32_16x16x32_bf16 v[120:123], v[158:161], v[170:173], 0
	v_mfma_f32_16x16x32_bf16 v[116:119], v[150:153], v[178:181], 0
	v_mfma_f32_16x16x32_bf16 v[108:111], v[158:161], v[178:181], 0
	v_mfma_f32_16x16x32_bf16 v[100:103], v[150:153], v[186:189], 0
	v_mfma_f32_16x16x32_bf16 v[92:95], v[158:161], v[186:189], 0
	v_mfma_f32_16x16x32_bf16 v[84:87], v[150:153], v[194:197], 0
	v_mfma_f32_16x16x32_bf16 v[76:79], v[158:161], v[194:197], 0
	v_mfma_f32_16x16x32_bf16 v[124:127], v[154:157], v[174:177], v[124:127]
	v_mfma_f32_16x16x32_bf16 v[120:123], v[166:169], v[174:177], v[120:123]
	v_mfma_f32_16x16x32_bf16 v[116:119], v[154:157], v[182:185], v[116:119]
	v_mfma_f32_16x16x32_bf16 v[108:111], v[166:169], v[182:185], v[108:111]
	v_mfma_f32_16x16x32_bf16 v[100:103], v[154:157], v[190:193], v[100:103]
	v_mfma_f32_16x16x32_bf16 v[92:95], v[166:169], v[190:193], v[92:95]
	v_mfma_f32_16x16x32_bf16 v[84:87], v[154:157], v[198:201], v[84:87]
	v_mfma_f32_16x16x32_bf16 v[76:79], v[166:169], v[198:201], v[76:79]
	v_mfma_f32_16x16x32_bf16 v[112:115], v[202:205], v[170:173], 0
	v_mfma_f32_16x16x32_bf16 v[104:107], v[210:213], v[170:173], 0
	v_mfma_f32_16x16x32_bf16 v[96:99], v[202:205], v[178:181], 0
	v_mfma_f32_16x16x32_bf16 v[88:91], v[210:213], v[178:181], 0
	v_mfma_f32_16x16x32_bf16 v[80:83], v[202:205], v[186:189], 0
	v_mfma_f32_16x16x32_bf16 v[72:75], v[210:213], v[186:189], 0
	v_mfma_f32_16x16x32_bf16 v[68:71], v[202:205], v[194:197], 0
	v_mfma_f32_16x16x32_bf16 v[64:67], v[210:213], v[194:197], 0
	v_mfma_f32_16x16x32_bf16 v[112:115], v[206:209], v[174:177], v[112:115]
	v_mfma_f32_16x16x32_bf16 v[104:107], v[214:217], v[174:177], v[104:107]
	v_mfma_f32_16x16x32_bf16 v[96:99], v[206:209], v[182:185], v[96:99]
	v_mfma_f32_16x16x32_bf16 v[88:91], v[214:217], v[182:185], v[88:91]
	v_mfma_f32_16x16x32_bf16 v[80:83], v[206:209], v[190:193], v[80:83]
	v_mfma_f32_16x16x32_bf16 v[72:75], v[214:217], v[190:193], v[72:75]
	v_mfma_f32_16x16x32_bf16 v[68:71], v[206:209], v[198:201], v[68:71]
	v_mfma_f32_16x16x32_bf16 v[64:67], v[214:217], v[198:201], v[64:67]
	s_barrier
	ds_read_b128 v[170:173], v163 offset:16384
	ds_read_b128 v[174:177], v163 offset:17408
	ds_read_b128 v[178:181], v163 offset:18432
	ds_read_b128 v[182:185], v163 offset:19456
	ds_read_b128 v[186:189], v163 offset:20480
	ds_read_b128 v[190:193], v163 offset:21504
	ds_read_b128 v[194:197], v163 offset:22528
	ds_read_b128 v[198:201], v163 offset:23552
	s_add_i32 s45, s66, s21
	s_mov_b32 m0, s45
	v_lshl_add_u64 v[218:219], s[54:55], 0, v[138:139]
	global_load_lds_dwordx4 v[218:219], off
	s_add_i32 m0, s45, 0x2000
	v_lshl_add_u64 v[220:221], s[54:55], 0, v[142:143]
	global_load_lds_dwordx4 v[220:221], off
	s_mov_b32 m0, s33
	v_lshl_add_u64 v[222:223], s[56:57], 0, v[136:137]
	global_load_lds_dwordx4 v[222:223], off
	s_mov_b32 m0, s35
	v_lshl_add_u64 v[224:225], s[56:57], 0, v[140:141]
	global_load_lds_dwordx4 v[224:225], off
	s_add_u32 s78, s54, 0x40000
	s_addc_u32 s79, s55, 0
	s_add_i32 s45, s67, s21
	s_mov_b32 m0, s45
	v_lshl_add_u64 v[240:241], s[78:79], 0, v[138:139]
	global_load_lds_dwordx4 v[240:241], off
	s_add_i32 m0, s45, 0x2000
	v_lshl_add_u64 v[240:241], s[78:79], 0, v[142:143]
	global_load_lds_dwordx4 v[240:241], off
	s_cmp_eq_u32 s99, 0
	s_cbranch_scc1 .Lrw4_1s
	s_waitcnt vmcnt(24) lgkmcnt(0)
	s_branch .Lrw4_1d

; #define PG8_STAGE(bufoff, gbase, voff) do { _Pragma("unroll") for (int _i = 0; _i < 2; ++_i) \
;         __builtin_amdgcn_global_load_lds((const unsigned*)((const char*)(gbase) + (voff)[_i]), (LAS unsigned*)(lds + (bufoff) + ldsw + _i * 8192), 16, 0, 0); } while (0)
; #define PG8_LDA(dst, b, h) do { _Pragma("unroll") for (int m = 0; m < 4; ++m) _Pragma("unroll") for (int k = 0; k < 2; ++k) dst[m][k] = *(const LAS bf16x8*)(lds + PG8_SA(b, h) + aoff + m * 2048 + k * 1024); } while (0)
; #define PG8_LDB(dst, b, h) do { _Pragma("unroll") for (int n = 0; n < 2; ++n) _Pragma("unroll") for (int k = 0; k < 2; ++k) dst[n][k] = *(const LAS bf16x8*)(lds + PG8_SB(b, h) + boff + n * 2048 + k * 1024); } while (0)
; #define PG8_MMA(ai, bj, At, Bt) do { __builtin_amdgcn_s_setprio(1); _Pragma("unroll") for (int m = 0; m < 4; ++m) _Pragma("unroll") for (int n = 0; n < 2; ++n) _Pragma("unroll") for (int k = 0; k < 2; ++k) \
;         acc[ai][bj][m][n] = __builtin_amdgcn_mfma_f32_16x16x32_bf16(Bt[n][k], At[m][k], acc[ai][bj][m][n], 0, 0, 0); __builtin_amdgcn_s_setprio(0); } while (0)
; #define PG8_WAIT_V(n) asm volatile("s_waitcnt vmcnt(" #n ")" ::: "memory")
; #define PG8_WAIT_L(n) asm volatile("s_waitcnt lgkmcnt(" #n ")" ::: "memory")
; #define PG8_BAR __builtin_amdgcn_s_barrier()
; #define PG8_SCHED __builtin_amdgcn_sched_barrier(0)
; template <class Epi>
; __device__ __forceinline__ void gemm_phase(LAS unsigned char* lds, const Gemm g, const StaticOrder& S, const Epi& E) {
;     ...
;             PG8_BAR; PG8_WAIT_L(0); PG8_MMA(0, 1, At, B1); PG8_BAR;
;             PG8_LDA(At, 0, 1); PG8_STAGE(PG8_SA(0, 0), a2, voffA);
;             PG8_BAR; PG8_WAIT_L(0); PG8_MMA(1, 0, At, B0); PG8_BAR; PG8_SCHED;
;             PG8_STAGE(PG8_SB(0, 1), b2 + hstepB, voffB);
;             PG8_WAIT_V(6); PG8_BAR; PG8_MMA(1, 1, At, B1); PG8_BAR;
;             PG8_LDB(B0, 1, 0); PG8_SCHED; PG8_LDA(At, 1, 0); PG8_STAGE(PG8_SA(0, 1), a2 + hstepA, voffA);
;             PG8_WAIT_L(8); PG8_BAR; PG8_WAIT_L(0); PG8_MMA(0, 0, At, B0); PG8_BAR; PG8_SCHED;
.Lrw4_1d:
	s_mov_b32 s99, 1
	s_barrier
	v_mfma_f32_16x16x32_bf16 v[60:63], v[150:153], v[170:173], 0
	v_mfma_f32_16x16x32_bf16 v[56:59], v[158:161], v[170:173], 0
	v_mfma_f32_16x16x32_bf16 v[52:55], v[150:153], v[178:181], 0
	v_mfma_f32_16x16x32_bf16 v[44:47], v[158:161], v[178:181], 0
	v_mfma_f32_16x16x32_bf16 v[36:39], v[150:153], v[186:189], 0
	v_mfma_f32_16x16x32_bf16 v[28:31], v[158:161], v[186:189], 0
	v_mfma_f32_16x16x32_bf16 v[20:23], v[150:153], v[194:197], 0
	v_mfma_f32_16x16x32_bf16 v[12:15], v[158:161], v[194:197], 0
	v_mfma_f32_16x16x32_bf16 v[60:63], v[154:157], v[174:177], v[60:63]
	v_mfma_f32_16x16x32_bf16 v[56:59], v[166:169], v[174:177], v[56:59]
	v_mfma_f32_16x16x32_bf16 v[52:55], v[154:157], v[182:185], v[52:55]
	v_mfma_f32_16x16x32_bf16 v[44:47], v[166:169], v[182:185], v[44:47]
	v_mfma_f32_16x16x32_bf16 v[36:39], v[154:157], v[190:193], v[36:39]
	v_mfma_f32_16x16x32_bf16 v[28:31], v[166:169], v[190:193], v[28:31]
	v_mfma_f32_16x16x32_bf16 v[20:23], v[154:157], v[198:201], v[20:23]
	v_mfma_f32_16x16x32_bf16 v[12:15], v[166:169], v[198:201], v[12:15]
	v_mfma_f32_16x16x32_bf16 v[48:51], v[202:205], v[170:173], 0
	v_mfma_f32_16x16x32_bf16 v[40:43], v[210:213], v[170:173], 0
	v_mfma_f32_16x16x32_bf16 v[32:35], v[202:205], v[178:181], 0
	v_mfma_f32_16x16x32_bf16 v[24:27], v[210:213], v[178:181], 0
	v_mfma_f32_16x16x32_bf16 v[16:19], v[202:205], v[186:189], 0
	v_mfma_f32_16x16x32_bf16 v[8:11], v[210:213], v[186:189], 0
	v_mfma_f32_16x16x32_bf16 v[4:7], v[202:205], v[194:197], 0
	v_mfma_f32_16x16x32_bf16 v[0:3], v[210:213], v[194:197], 0
	v_mfma_f32_16x16x32_bf16 v[48:51], v[206:209], v[174:177], v[48:51]
	v_mfma_f32_16x16x32_bf16 v[40:43], v[214:217], v[174:177], v[40:43]
	v_mfma_f32_16x16x32_bf16 v[32:35], v[206:209], v[182:185], v[32:35]
	v_mfma_f32_16x16x32_bf16 v[24:27], v[214:217], v[182:185], v[24:27]
	v_mfma_f32_16x16x32_bf16 v[16:19], v[206:209], v[190:193], v[16:19]
	v_mfma_f32_16x16x32_bf16 v[8:11], v[214:217], v[190:193], v[8:11]
	v_mfma_f32_16x16x32_bf16 v[4:7], v[206:209], v[198:201], v[4:7]
	v_mfma_f32_16x16x32_bf16 v[0:3], v[214:217], v[198:201], v[0:3]
	s_barrier
	s_add_i32 s45, 0, 0x18000
	v_add_u32_e32 v165, s45, v135
	ds_read_b128 v[150:153], v165
	ds_read_b128 v[154:157], v165 offset:1024
	ds_read_b128 v[158:161], v165 offset:2048
	ds_read_b128 v[166:169], v165 offset:3072
	ds_read_b128 v[170:173], v163 offset:32768
	ds_read_b128 v[174:177], v163 offset:33792
	ds_read_b128 v[178:181], v163 offset:34816
	ds_read_b128 v[182:185], v163 offset:35840
	ds_read_b128 v[186:189], v163 offset:36864
	ds_read_b128 v[190:193], v163 offset:37888
	ds_read_b128 v[194:197], v163 offset:38912
	ds_read_b128 v[198:201], v163 offset:39936
	s_add_i32 s98, 0, 0x1c000
	v_add_u32_e32 v246, s98, v135
	ds_read_b128 v[202:205], v246
	ds_read_b128 v[206:209], v246 offset:1024
	ds_read_b128 v[210:213], v246 offset:2048
	ds_read_b128 v[214:217], v246 offset:3072
	s_add_u32 s56, s56, 0x40000
	s_addc_u32 s57, s57, 0
	s_mov_b32 m0, s58
	v_lshl_add_u64 v[244:245], s[56:57], 0, v[136:137]
	global_load_lds_dwordx4 v[244:245], off
	s_mov_b32 m0, s59
	v_lshl_add_u64 v[244:245], s[56:57], 0, v[140:141]
	global_load_lds_dwordx4 v[244:245], off
	s_waitcnt vmcnt(8) lgkmcnt(0)
	s_barrier
	v_mfma_f32_16x16x32_bf16 v[124:127], v[150:153], v[170:173], v[124:127]
	v_mfma_f32_16x16x32_bf16 v[120:123], v[158:161], v[170:173], v[120:123]
	v_mfma_f32_16x16x32_bf16 v[116:119], v[150:153], v[178:181], v[116:119]
	v_mfma_f32_16x16x32_bf16 v[108:111], v[158:161], v[178:181], v[108:111]
	v_mfma_f32_16x16x32_bf16 v[100:103], v[150:153], v[186:189], v[100:103]
	v_mfma_f32_16x16x32_bf16 v[92:95], v[158:161], v[186:189], v[92:95]
	v_mfma_f32_16x16x32_bf16 v[84:87], v[150:153], v[194:197], v[84:87]
	v_mfma_f32_16x16x32_bf16 v[76:79], v[158:161], v[194:197], v[76:79]
	v_mfma_f32_16x16x32_bf16 v[124:127], v[154:157], v[174:177], v[124:127]
	v_mfma_f32_16x16x32_bf16 v[120:123], v[166:169], v[174:177], v[120:123]
	v_mfma_f32_16x16x32_bf16 v[116:119], v[154:157], v[182:185], v[116:119]
	v_mfma_f32_16x16x32_bf16 v[108:111], v[166:169], v[182:185], v[108:111]
	v_mfma_f32_16x16x32_bf16 v[100:103], v[154:157], v[190:193], v[100:103]
	v_mfma_f32_16x16x32_bf16 v[92:95], v[166:169], v[190:193], v[92:95]
	v_mfma_f32_16x16x32_bf16 v[84:87], v[154:157], v[198:201], v[84:87]
	v_mfma_f32_16x16x32_bf16 v[76:79], v[166:169], v[198:201], v[76:79]
	v_mfma_f32_16x16x32_bf16 v[112:115], v[202:205], v[170:173], v[112:115]
	v_mfma_f32_16x16x32_bf16 v[104:107], v[210:213], v[170:173], v[104:107]
	v_mfma_f32_16x16x32_bf16 v[96:99], v[202:205], v[178:181], v[96:99]
	v_mfma_f32_16x16x32_bf16 v[88:91], v[210:213], v[178:181], v[88:91]
	v_mfma_f32_16x16x32_bf16 v[80:83], v[202:205], v[186:189], v[80:83]
	v_mfma_f32_16x16x32_bf16 v[72:75], v[210:213], v[186:189], v[72:75]
	v_mfma_f32_16x16x32_bf16 v[68:71], v[202:205], v[194:197], v[68:71]
	v_mfma_f32_16x16x32_bf16 v[64:67], v[210:213], v[194:197], v[64:67]
	v_mfma_f32_16x16x32_bf16 v[112:115], v[206:209], v[174:177], v[112:115]
	v_mfma_f32_16x16x32_bf16 v[104:107], v[214:217], v[174:177], v[104:107]
	v_mfma_f32_16x16x32_bf16 v[96:99], v[206:209], v[182:185], v[96:99]
	v_mfma_f32_16x16x32_bf16 v[88:91], v[214:217], v[182:185], v[88:91]
	v_mfma_f32_16x16x32_bf16 v[80:83], v[206:209], v[190:193], v[80:83]
	v_mfma_f32_16x16x32_bf16 v[72:75], v[214:217], v[190:193], v[72:75]
	v_mfma_f32_16x16x32_bf16 v[68:71], v[206:209], v[198:201], v[68:71]
	v_mfma_f32_16x16x32_bf16 v[64:67], v[214:217], v[198:201], v[64:67]
	s_barrier
; #define PG8_STAGE(bufoff, gbase, voff) do { _Pragma("unroll") for (int _i = 0; _i < 2; ++_i) \
;         __builtin_amdgcn_global_load_lds((const unsigned*)((const char*)(gbase) + (voff)[_i]), (LAS unsigned*)(lds + (bufoff) + ldsw + _i * 8192), 16, 0, 0); } while (0)
; #define PG8_LDA(dst, b, h) do { _Pragma("unroll") for (int m = 0; m < 4; ++m) _Pragma("unroll") for (int k = 0; k < 2; ++k) dst[m][k] = *(const LAS bf16x8*)(lds + PG8_SA(b, h) + aoff + m * 2048 + k * 1024); } while (0)
; #define PG8_LDB(dst, b, h) do { _Pragma("unroll") for (int n = 0; n < 2; ++n) _Pragma("unroll") for (int k = 0; k < 2; ++k) dst[n][k] = *(const LAS bf16x8*)(lds + PG8_SB(b, h) + boff + n * 2048 + k * 1024); } while (0)
; #define PG8_MMA(ai, bj, At, Bt) do { __builtin_amdgcn_s_setprio(1); _Pragma("unroll") for (int m = 0; m < 4; ++m) _Pragma("unroll") for (int n = 0; n < 2; ++n) _Pragma("unroll") for (int k = 0; k < 2; ++k) \
;         acc[ai][bj][m][n] = __builtin_amdgcn_mfma_f32_16x16x32_bf16(Bt[n][k], At[m][k], acc[ai][bj][m][n], 0, 0, 0); __builtin_amdgcn_s_setprio(0); } while (0)
; #define PG8_WAIT_V(n) asm volatile("s_waitcnt vmcnt(" #n ")" ::: "memory")
; #define PG8_WAIT_L(n) asm volatile("s_waitcnt lgkmcnt(" #n ")" ::: "memory")
; #define PG8_BAR __builtin_amdgcn_s_barrier()
; #define PG8_SCHED __builtin_amdgcn_sched_barrier(0)
; template <class Epi>
; __device__ __forceinline__ void gemm_phase(LAS unsigned char* lds, const Gemm g, const StaticOrder& S, const Epi& E) {
;     ...
;             PG8_LDB(B1, 1, 1); PG8_STAGE(PG8_SB(1, 0), b3, voffB);
;             PG8_BAR; PG8_WAIT_L(0); PG8_MMA(0, 1, At, B1); PG8_BAR;
;             PG8_LDA(At, 1, 1); PG8_STAGE(PG8_SA(1, 0), a3, voffA);
;             PG8_BAR; PG8_WAIT_L(0); PG8_MMA(1, 0, At, B0); PG8_BAR; PG8_SCHED;
;             PG8_STAGE(PG8_SB(1, 1), b3 + hstepB, voffB);
;             PG8_WAIT_V(6); PG8_BAR; PG8_MMA(1, 1, At, B1); PG8_BAR;
	ds_read_b128 v[170:173], v163 offset:49152
	ds_read_b128 v[174:177], v163 offset:50176
	ds_read_b128 v[178:181], v163 offset:51200
	ds_read_b128 v[182:185], v163 offset:52224
	ds_read_b128 v[186:189], v163 offset:53248
	ds_read_b128 v[190:193], v163 offset:54272
	ds_read_b128 v[194:197], v163 offset:55296
	ds_read_b128 v[198:201], v163 offset:56320
	s_add_i32 s45, s45, s21
	s_mov_b32 m0, s45
	v_lshl_add_u64 v[218:219], v[218:219], 0, s[12:13]
	global_load_lds_dwordx4 v[218:219], off
	s_add_i32 m0, s45, 0x2000
	v_lshl_add_u64 v[218:219], v[220:221], 0, s[12:13]
	global_load_lds_dwordx4 v[218:219], off
	s_mov_b32 m0, s60
	v_lshl_add_u64 v[218:219], v[222:223], 0, s[12:13]
	global_load_lds_dwordx4 v[218:219], off
	s_mov_b32 m0, s61
	v_lshl_add_u64 v[218:219], v[224:225], 0, s[12:13]
	global_load_lds_dwordx4 v[218:219], off
	s_add_u32 s54, s54, 0x40080
	s_addc_u32 s55, s55, 0
	s_add_i32 s45, s98, s21
	s_mov_b32 m0, s45
	v_lshl_add_u64 v[240:241], s[54:55], 0, v[138:139]
	global_load_lds_dwordx4 v[240:241], off
	s_add_i32 m0, s45, 0x2000
	v_lshl_add_u64 v[240:241], s[54:55], 0, v[142:143]
	global_load_lds_dwordx4 v[240:241], off
	s_waitcnt vmcnt(8) lgkmcnt(0)
	s_barrier
	v_mfma_f32_16x16x32_bf16 v[60:63], v[150:153], v[170:173], v[60:63]
	v_mfma_f32_16x16x32_bf16 v[56:59], v[158:161], v[170:173], v[56:59]
	v_mfma_f32_16x16x32_bf16 v[52:55], v[150:153], v[178:181], v[52:55]
	v_mfma_f32_16x16x32_bf16 v[44:47], v[158:161], v[178:181], v[44:47]
	v_mfma_f32_16x16x32_bf16 v[36:39], v[150:153], v[186:189], v[36:39]
	v_mfma_f32_16x16x32_bf16 v[28:31], v[158:161], v[186:189], v[28:31]
	v_mfma_f32_16x16x32_bf16 v[20:23], v[150:153], v[194:197], v[20:23]
	v_mfma_f32_16x16x32_bf16 v[12:15], v[158:161], v[194:197], v[12:15]
	v_mfma_f32_16x16x32_bf16 v[60:63], v[154:157], v[174:177], v[60:63]
	v_mfma_f32_16x16x32_bf16 v[56:59], v[166:169], v[174:177], v[56:59]
	v_mfma_f32_16x16x32_bf16 v[52:55], v[154:157], v[182:185], v[52:55]
	v_mfma_f32_16x16x32_bf16 v[44:47], v[166:169], v[182:185], v[44:47]
	v_mfma_f32_16x16x32_bf16 v[36:39], v[154:157], v[190:193], v[36:39]
	v_mfma_f32_16x16x32_bf16 v[28:31], v[166:169], v[190:193], v[28:31]
	v_mfma_f32_16x16x32_bf16 v[20:23], v[154:157], v[198:201], v[20:23]
	v_mfma_f32_16x16x32_bf16 v[12:15], v[166:169], v[198:201], v[12:15]
	v_mfma_f32_16x16x32_bf16 v[48:51], v[202:205], v[170:173], v[48:51]
	v_mfma_f32_16x16x32_bf16 v[40:43], v[210:213], v[170:173], v[40:43]
	v_mfma_f32_16x16x32_bf16 v[32:35], v[202:205], v[178:181], v[32:35]
	v_mfma_f32_16x16x32_bf16 v[24:27], v[210:213], v[178:181], v[24:27]
	v_mfma_f32_16x16x32_bf16 v[16:19], v[202:205], v[186:189], v[16:19]
	v_mfma_f32_16x16x32_bf16 v[8:11], v[210:213], v[186:189], v[8:11]
	v_mfma_f32_16x16x32_bf16 v[4:7], v[202:205], v[194:197], v[4:7]
	v_mfma_f32_16x16x32_bf16 v[0:3], v[210:213], v[194:197], v[0:3]
	v_mfma_f32_16x16x32_bf16 v[48:51], v[206:209], v[174:177], v[48:51]
	v_mfma_f32_16x16x32_bf16 v[40:43], v[214:217], v[174:177], v[40:43]
	v_mfma_f32_16x16x32_bf16 v[32:35], v[206:209], v[182:185], v[32:35]
	v_mfma_f32_16x16x32_bf16 v[24:27], v[214:217], v[182:185], v[24:27]
	v_mfma_f32_16x16x32_bf16 v[16:19], v[206:209], v[190:193], v[16:19]
	v_mfma_f32_16x16x32_bf16 v[8:11], v[214:217], v[190:193], v[8:11]
	v_mfma_f32_16x16x32_bf16 v[4:7], v[206:209], v[198:201], v[4:7]
	v_mfma_f32_16x16x32_bf16 v[0:3], v[214:217], v[198:201], v[0:3]
	s_add_u32 s50, s50, 0x100
	s_addc_u32 s51, s51, 0
	s_add_u32 s41, s41, 0x100
	s_addc_u32 s43, s43, 0
	s_cmp_ge_i32 s77, s76
	s_mov_b32 s45, s77
	s_barrier
